# code placement: hot loop heads (6 GEMM K-loops, 2 attention loops) aligned to 64 bytes
# baseline (speedup 1.0000x reference)
.LBB0_757:
	s_ashr_i32 s17, s16, 31
	s_lshl_b64 s[18:19], s[16:17], 20
	s_add_u32 s18, s35, s18
	s_addc_u32 s19, s40, s19
	s_and_b64 s[20:21], s[4:5], exec
	s_cselect_b32 s17, s19, s29
	s_cselect_b32 s23, s18, s28
	s_ashr_i32 s15, s14, 31
	s_lshl_b64 s[20:21], s[14:15], 19
	s_add_u32 s20, s38, s20
	s_addc_u32 s21, s39, s21
	s_and_b64 s[30:31], s[4:5], exec
	s_cselect_b32 s15, s21, s27
	s_cselect_b32 s25, s20, s26
	s_add_u32 s52, s26, 0x100
	s_addc_u32 s53, s27, 0
	s_add_u32 s26, s28, 0x80080
	s_addc_u32 s27, s29, 0
	s_mov_b32 s54, -2
	s_waitcnt lgkmcnt(0)
	s_add_u32 s28, s26, 0xfff80080
	s_addc_u32 s29, s27, -1
	s_add_i32 s55, 0, 0x10000
	s_cmp_eq_u32 s54, 12
	s_cselect_b32 s31, s17, s29
	s_cselect_b32 s30, s23, s28
	s_cselect_b32 s29, s15, s53
	s_cselect_b32 s28, s25, s52
	s_add_i32 s58, 0, 0x14000
	v_add_u32_e32 v156, s55, v145
	v_add_u32_e32 v172, s58, v145
	ds_read_b128 v[140:143], v156
	ds_read_b128 v[148:151], v156 offset:1024
	ds_read_b128 v[152:155], v156 offset:2048
	ds_read_b128 v[156:159], v156 offset:3072
	ds_read_b128 v[160:163], v172
	ds_read_b128 v[164:167], v172 offset:1024
	ds_read_b128 v[168:171], v172 offset:2048
	ds_read_b128 v[172:175], v172 offset:3072
	s_add_i32 m0, s42, 0xc000
	ds_read_b128 v[176:179], v147
	ds_read_b128 v[180:183], v147 offset:1024
	ds_read_b128 v[184:187], v147 offset:2048
	ds_read_b128 v[208:211], v147 offset:3072
	ds_read_b128 v[230:233], v147 offset:4096
	ds_read_b128 v[234:237], v147 offset:5120
	ds_read_b128 v[238:241], v147 offset:6144
	ds_read_b128 v[242:245], v147 offset:7168
	global_load_lds_dwordx4 v138, s[26:27]
	s_add_i32 m0, s42, 0xe000
	s_nop 0
	global_load_lds_dwordx4 v136, s[26:27]
	s_waitcnt vmcnt(8)
	s_waitcnt lgkmcnt(0)
	s_barrier
	s_setprio 1
	s_waitcnt lgkmcnt(0)
	v_mfma_f32_16x16x32_bf16 v[126:129], v[140:143], v[176:179], 0
	v_mfma_f32_16x16x32_bf16 v[122:125], v[152:155], v[176:179], 0
	v_mfma_f32_16x16x32_bf16 v[108:111], v[140:143], v[184:187], 0
	v_mfma_f32_16x16x32_bf16 v[104:107], v[152:155], v[184:187], 0
	v_mfma_f32_16x16x32_bf16 v[92:95], v[140:143], v[230:233], 0
	v_mfma_f32_16x16x32_bf16 v[88:91], v[152:155], v[230:233], 0
	v_mfma_f32_16x16x32_bf16 v[76:79], v[140:143], v[238:241], 0
	v_mfma_f32_16x16x32_bf16 v[72:75], v[152:155], v[238:241], 0
	v_mfma_f32_16x16x32_bf16 v[126:129], v[148:151], v[180:183], v[126:129]
	v_mfma_f32_16x16x32_bf16 v[122:125], v[156:159], v[180:183], v[122:125]
	v_mfma_f32_16x16x32_bf16 v[108:111], v[148:151], v[208:211], v[108:111]
	v_mfma_f32_16x16x32_bf16 v[104:107], v[156:159], v[208:211], v[104:107]
	v_mfma_f32_16x16x32_bf16 v[92:95], v[148:151], v[234:237], v[92:95]
	v_mfma_f32_16x16x32_bf16 v[88:91], v[156:159], v[234:237], v[88:91]
	v_mfma_f32_16x16x32_bf16 v[76:79], v[148:151], v[242:245], v[76:79]
	v_mfma_f32_16x16x32_bf16 v[72:75], v[156:159], v[242:245], v[72:75]
	s_setprio 0
	s_setprio 1
	v_mfma_f32_16x16x32_bf16 v[118:121], v[160:163], v[176:179], 0
	v_mfma_f32_16x16x32_bf16 v[114:117], v[168:171], v[176:179], 0
	v_mfma_f32_16x16x32_bf16 v[100:103], v[160:163], v[184:187], 0
	v_mfma_f32_16x16x32_bf16 v[96:99], v[168:171], v[184:187], 0
	v_mfma_f32_16x16x32_bf16 v[84:87], v[160:163], v[230:233], 0
	v_mfma_f32_16x16x32_bf16 v[80:83], v[168:171], v[230:233], 0
	v_mfma_f32_16x16x32_bf16 v[68:71], v[160:163], v[238:241], 0
	v_mfma_f32_16x16x32_bf16 v[64:67], v[168:171], v[238:241], 0
	v_mfma_f32_16x16x32_bf16 v[118:121], v[164:167], v[180:183], v[118:121]
	v_mfma_f32_16x16x32_bf16 v[114:117], v[172:175], v[180:183], v[114:117]
	v_mfma_f32_16x16x32_bf16 v[100:103], v[164:167], v[208:211], v[100:103]
	v_mfma_f32_16x16x32_bf16 v[96:99], v[172:175], v[208:211], v[96:99]
	v_mfma_f32_16x16x32_bf16 v[84:87], v[164:167], v[234:237], v[84:87]
	v_mfma_f32_16x16x32_bf16 v[80:83], v[172:175], v[234:237], v[80:83]
	v_mfma_f32_16x16x32_bf16 v[68:71], v[164:167], v[242:245], v[68:71]
	v_mfma_f32_16x16x32_bf16 v[64:67], v[172:175], v[242:245], v[64:67]
	s_setprio 0
	s_barrier
	s_add_i32 s55, s55, s41
	s_mov_b32 m0, s55
	ds_read_b128 v[176:179], v147 offset:16384
	ds_read_b128 v[180:183], v147 offset:17408
	ds_read_b128 v[184:187], v147 offset:18432
	ds_read_b128 v[208:211], v147 offset:19456
	ds_read_b128 v[230:233], v147 offset:20480
	ds_read_b128 v[234:237], v147 offset:21504
	ds_read_b128 v[238:241], v147 offset:22528
	ds_read_b128 v[242:245], v147 offset:23552
	global_load_lds_dwordx4 v112, s[28:29]
	s_add_i32 m0, s55, 0x2000
	s_add_u32 s56, s28, 0x40000
	v_lshl_add_u64 v[212:213], s[28:29], 0, v[134:135]
	s_addc_u32 s57, s29, 0
	s_add_i32 s55, s58, s41
	global_load_lds_dwordx4 v134, s[28:29]
	s_mov_b32 m0, s55
	v_lshl_add_u64 v[246:247], s[30:31], 0, v[132:133]
	global_load_lds_dwordx4 v112, s[56:57]
	s_add_i32 m0, s55, 0x2000
	s_nop 0
	global_load_lds_dwordx4 v134, s[56:57]
	v_lshl_add_u64 v[228:229], s[30:31], 0, v[130:131]
	s_mov_b32 m0, s42
	s_nop 0
	global_load_lds_dwordx4 v130, s[30:31]
	s_mov_b32 m0, s43
	s_nop 0
	global_load_lds_dwordx4 v132, s[30:31]
	s_waitcnt vmcnt(8)
	s_waitcnt lgkmcnt(0)
	s_barrier
	s_setprio 1
	s_waitcnt lgkmcnt(0)
	v_mfma_f32_16x16x32_bf16 v[60:63], v[140:143], v[176:179], 0
	v_mfma_f32_16x16x32_bf16 v[56:59], v[152:155], v[176:179], 0
	v_mfma_f32_16x16x32_bf16 v[44:47], v[140:143], v[184:187], 0
	v_mfma_f32_16x16x32_bf16 v[40:43], v[152:155], v[184:187], 0
	v_mfma_f32_16x16x32_bf16 v[28:31], v[140:143], v[230:233], 0
	v_mfma_f32_16x16x32_bf16 v[24:27], v[152:155], v[230:233], 0
	v_mfma_f32_16x16x32_bf16 v[12:15], v[140:143], v[238:241], 0
	v_mfma_f32_16x16x32_bf16 v[8:11], v[152:155], v[238:241], 0
	v_mfma_f32_16x16x32_bf16 v[60:63], v[148:151], v[180:183], v[60:63]
	v_mfma_f32_16x16x32_bf16 v[56:59], v[156:159], v[180:183], v[56:59]
	v_mfma_f32_16x16x32_bf16 v[44:47], v[148:151], v[208:211], v[44:47]
	v_mfma_f32_16x16x32_bf16 v[40:43], v[156:159], v[208:211], v[40:43]
	v_mfma_f32_16x16x32_bf16 v[28:31], v[148:151], v[234:237], v[28:31]
	v_mfma_f32_16x16x32_bf16 v[24:27], v[156:159], v[234:237], v[24:27]
	v_mfma_f32_16x16x32_bf16 v[12:15], v[148:151], v[242:245], v[12:15]
	v_mfma_f32_16x16x32_bf16 v[8:11], v[156:159], v[242:245], v[8:11]
	s_setprio 0
	s_setprio 1
	v_mfma_f32_16x16x32_bf16 v[52:55], v[160:163], v[176:179], 0
	v_mfma_f32_16x16x32_bf16 v[48:51], v[168:171], v[176:179], 0
	v_mfma_f32_16x16x32_bf16 v[36:39], v[160:163], v[184:187], 0
	v_mfma_f32_16x16x32_bf16 v[32:35], v[168:171], v[184:187], 0
	v_mfma_f32_16x16x32_bf16 v[20:23], v[160:163], v[230:233], 0
	v_mfma_f32_16x16x32_bf16 v[16:19], v[168:171], v[230:233], 0
	v_mfma_f32_16x16x32_bf16 v[4:7], v[160:163], v[238:241], 0
	v_mfma_f32_16x16x32_bf16 v[0:3], v[168:171], v[238:241], 0
	v_mfma_f32_16x16x32_bf16 v[52:55], v[164:167], v[180:183], v[52:55]
	v_mfma_f32_16x16x32_bf16 v[48:51], v[172:175], v[180:183], v[48:51]
	v_mfma_f32_16x16x32_bf16 v[36:39], v[164:167], v[208:211], v[36:39]
	v_mfma_f32_16x16x32_bf16 v[32:35], v[172:175], v[208:211], v[32:35]
	v_mfma_f32_16x16x32_bf16 v[20:23], v[164:167], v[234:237], v[20:23]
	v_mfma_f32_16x16x32_bf16 v[16:19], v[172:175], v[234:237], v[16:19]
	v_mfma_f32_16x16x32_bf16 v[4:7], v[164:167], v[242:245], v[4:7]
	v_mfma_f32_16x16x32_bf16 v[0:3], v[172:175], v[242:245], v[0:3]
	s_setprio 0
	s_barrier
	s_add_i32 s55, 0, 0x18000
	s_add_i32 s56, 0, 0x1c000
	v_add_u32_e32 v156, s55, v145
	v_add_u32_e32 v172, s56, v145
	ds_read_b128 v[140:143], v156
	ds_read_b128 v[148:151], v156 offset:1024
	ds_read_b128 v[152:155], v156 offset:2048
	ds_read_b128 v[156:159], v156 offset:3072
	ds_read_b128 v[160:163], v172
	ds_read_b128 v[164:167], v172 offset:1024
	ds_read_b128 v[168:171], v172 offset:2048
	ds_read_b128 v[172:175], v172 offset:3072
	s_add_u32 s30, s30, 0x80000
	s_addc_u32 s31, s31, 0
	s_mov_b32 m0, s44
	ds_read_b128 v[176:179], v147 offset:32768
	ds_read_b128 v[180:183], v147 offset:33792
	ds_read_b128 v[184:187], v147 offset:34816
	ds_read_b128 v[208:211], v147 offset:35840
	ds_read_b128 v[230:233], v147 offset:36864
	ds_read_b128 v[234:237], v147 offset:37888
	ds_read_b128 v[238:241], v147 offset:38912
	ds_read_b128 v[242:245], v147 offset:39936
	global_load_lds_dwordx4 v130, s[30:31]
	s_mov_b32 m0, s45
	s_nop 0
	global_load_lds_dwordx4 v132, s[30:31]
	s_waitcnt vmcnt(8)
	s_waitcnt lgkmcnt(0)
	s_barrier
	s_setprio 1
	s_waitcnt lgkmcnt(0)
	v_mfma_f32_16x16x32_bf16 v[126:129], v[140:143], v[176:179], v[126:129]
	v_mfma_f32_16x16x32_bf16 v[122:125], v[152:155], v[176:179], v[122:125]
	v_mfma_f32_16x16x32_bf16 v[108:111], v[140:143], v[184:187], v[108:111]
	v_mfma_f32_16x16x32_bf16 v[104:107], v[152:155], v[184:187], v[104:107]
	v_mfma_f32_16x16x32_bf16 v[92:95], v[140:143], v[230:233], v[92:95]
	v_mfma_f32_16x16x32_bf16 v[88:91], v[152:155], v[230:233], v[88:91]
	v_mfma_f32_16x16x32_bf16 v[76:79], v[140:143], v[238:241], v[76:79]
	v_mfma_f32_16x16x32_bf16 v[72:75], v[152:155], v[238:241], v[72:75]
	v_mfma_f32_16x16x32_bf16 v[126:129], v[148:151], v[180:183], v[126:129]
	v_mfma_f32_16x16x32_bf16 v[122:125], v[156:159], v[180:183], v[122:125]
	v_mfma_f32_16x16x32_bf16 v[108:111], v[148:151], v[208:211], v[108:111]
	v_mfma_f32_16x16x32_bf16 v[104:107], v[156:159], v[208:211], v[104:107]
	v_mfma_f32_16x16x32_bf16 v[92:95], v[148:151], v[234:237], v[92:95]
	v_mfma_f32_16x16x32_bf16 v[88:91], v[156:159], v[234:237], v[88:91]
	v_mfma_f32_16x16x32_bf16 v[76:79], v[148:151], v[242:245], v[76:79]
	v_mfma_f32_16x16x32_bf16 v[72:75], v[156:159], v[242:245], v[72:75]
	s_setprio 0
	s_setprio 1
	v_mfma_f32_16x16x32_bf16 v[118:121], v[160:163], v[176:179], v[118:121]
	v_mfma_f32_16x16x32_bf16 v[114:117], v[168:171], v[176:179], v[114:117]
	v_mfma_f32_16x16x32_bf16 v[100:103], v[160:163], v[184:187], v[100:103]
	v_mfma_f32_16x16x32_bf16 v[96:99], v[168:171], v[184:187], v[96:99]
	v_mfma_f32_16x16x32_bf16 v[84:87], v[160:163], v[230:233], v[84:87]
	v_mfma_f32_16x16x32_bf16 v[80:83], v[168:171], v[230:233], v[80:83]
	v_mfma_f32_16x16x32_bf16 v[68:71], v[160:163], v[238:241], v[68:71]
	v_mfma_f32_16x16x32_bf16 v[64:67], v[168:171], v[238:241], v[64:67]
	v_mfma_f32_16x16x32_bf16 v[118:121], v[164:167], v[180:183], v[118:121]
	v_mfma_f32_16x16x32_bf16 v[114:117], v[172:175], v[180:183], v[114:117]
	v_mfma_f32_16x16x32_bf16 v[100:103], v[164:167], v[208:211], v[100:103]
	v_mfma_f32_16x16x32_bf16 v[96:99], v[172:175], v[208:211], v[96:99]
	v_mfma_f32_16x16x32_bf16 v[84:87], v[164:167], v[234:237], v[84:87]
	v_mfma_f32_16x16x32_bf16 v[80:83], v[172:175], v[234:237], v[80:83]
	v_mfma_f32_16x16x32_bf16 v[68:71], v[164:167], v[242:245], v[68:71]
	v_mfma_f32_16x16x32_bf16 v[64:67], v[172:175], v[242:245], v[64:67]
	s_setprio 0
	s_barrier
	s_add_i32 s30, s55, s41
	s_mov_b32 m0, s30
	ds_read_b128 v[176:179], v147 offset:49152
	ds_read_b128 v[180:183], v147 offset:50176
	ds_read_b128 v[184:187], v147 offset:51200
	ds_read_b128 v[208:211], v147 offset:52224
	ds_read_b128 v[230:233], v147 offset:53248
	ds_read_b128 v[234:237], v147 offset:54272
	ds_read_b128 v[238:241], v147 offset:55296
	ds_read_b128 v[242:245], v147 offset:56320
	s_add_u32 s98, s28, 0x80
	s_addc_u32 s99, s29, 0
	global_load_lds_dwordx4 v112, s[98:99]
	s_add_i32 m0, s30, 0x2000
	s_add_u32 s28, s28, 0x40080
	v_lshl_add_u64 v[188:189], v[212:213], 0, s[96:97]
	s_addc_u32 s29, s29, 0
	s_add_i32 s30, s56, s41
	global_load_lds_dwordx4 v[188:189], off
	s_mov_b32 m0, s30
	s_nop 0
	global_load_lds_dwordx4 v112, s[28:29]
	s_add_i32 m0, s30, 0x2000
	s_nop 0
	global_load_lds_dwordx4 v134, s[28:29]
	v_lshl_add_u64 v[188:189], v[228:229], 0, s[96:97]
	s_mov_b32 m0, s47
	s_nop 0
	global_load_lds_dwordx4 v[188:189], off
	v_lshl_add_u64 v[188:189], v[246:247], 0, s[96:97]
	s_mov_b32 m0, s48
	s_nop 0
	global_load_lds_dwordx4 v[188:189], off
	s_waitcnt vmcnt(8)
	s_waitcnt lgkmcnt(0)
	s_barrier
	s_setprio 1
	s_waitcnt lgkmcnt(0)
	v_mfma_f32_16x16x32_bf16 v[60:63], v[140:143], v[176:179], v[60:63]
	v_mfma_f32_16x16x32_bf16 v[56:59], v[152:155], v[176:179], v[56:59]
	v_mfma_f32_16x16x32_bf16 v[44:47], v[140:143], v[184:187], v[44:47]
	v_mfma_f32_16x16x32_bf16 v[40:43], v[152:155], v[184:187], v[40:43]
	v_mfma_f32_16x16x32_bf16 v[28:31], v[140:143], v[230:233], v[28:31]
	v_mfma_f32_16x16x32_bf16 v[24:27], v[152:155], v[230:233], v[24:27]
	v_mfma_f32_16x16x32_bf16 v[12:15], v[140:143], v[238:241], v[12:15]
	v_mfma_f32_16x16x32_bf16 v[8:11], v[152:155], v[238:241], v[8:11]
	v_mfma_f32_16x16x32_bf16 v[60:63], v[148:151], v[180:183], v[60:63]
	v_mfma_f32_16x16x32_bf16 v[56:59], v[156:159], v[180:183], v[56:59]
	v_mfma_f32_16x16x32_bf16 v[44:47], v[148:151], v[208:211], v[44:47]
	v_mfma_f32_16x16x32_bf16 v[40:43], v[156:159], v[208:211], v[40:43]
	v_mfma_f32_16x16x32_bf16 v[28:31], v[148:151], v[234:237], v[28:31]
	v_mfma_f32_16x16x32_bf16 v[24:27], v[156:159], v[234:237], v[24:27]
	v_mfma_f32_16x16x32_bf16 v[12:15], v[148:151], v[242:245], v[12:15]
	v_mfma_f32_16x16x32_bf16 v[8:11], v[156:159], v[242:245], v[8:11]
	s_setprio 0
	s_setprio 1
	v_mfma_f32_16x16x32_bf16 v[52:55], v[160:163], v[176:179], v[52:55]
	v_mfma_f32_16x16x32_bf16 v[48:51], v[168:171], v[176:179], v[48:51]
	v_mfma_f32_16x16x32_bf16 v[36:39], v[160:163], v[184:187], v[36:39]
	v_mfma_f32_16x16x32_bf16 v[32:35], v[168:171], v[184:187], v[32:35]
	v_mfma_f32_16x16x32_bf16 v[20:23], v[160:163], v[230:233], v[20:23]
	v_mfma_f32_16x16x32_bf16 v[16:19], v[168:171], v[230:233], v[16:19]
	v_mfma_f32_16x16x32_bf16 v[4:7], v[160:163], v[238:241], v[4:7]
	v_mfma_f32_16x16x32_bf16 v[0:3], v[168:171], v[238:241], v[0:3]
	v_mfma_f32_16x16x32_bf16 v[52:55], v[164:167], v[180:183], v[52:55]
	v_mfma_f32_16x16x32_bf16 v[48:51], v[172:175], v[180:183], v[48:51]
	v_mfma_f32_16x16x32_bf16 v[36:39], v[164:167], v[208:211], v[36:39]
	v_mfma_f32_16x16x32_bf16 v[32:35], v[172:175], v[208:211], v[32:35]
	v_mfma_f32_16x16x32_bf16 v[20:23], v[164:167], v[234:237], v[20:23]
	v_mfma_f32_16x16x32_bf16 v[16:19], v[172:175], v[234:237], v[16:19]
	v_mfma_f32_16x16x32_bf16 v[4:7], v[164:167], v[242:245], v[4:7]
	v_mfma_f32_16x16x32_bf16 v[0:3], v[172:175], v[242:245], v[0:3]
	s_setprio 0
	s_barrier
	s_add_i32 s54, s54, 2
	s_add_u32 s52, s52, 0x100
	s_addc_u32 s53, s53, 0
	s_add_u32 s26, s26, 0x100
	s_addc_u32 s27, s27, 0
	s_cmp_gt_u32 s54, 13
	s_cbranch_scc0 .LBB0_758
	s_branch .Lpeel_exit_758
	.p2align 6

.LBB0_803:
	s_ashr_i32 s15, s14, 31
	s_lshl_b64 s[18:19], s[14:15], 20
	s_add_u32 s18, s38, s18
	s_addc_u32 s19, s39, s19
	s_and_b64 s[0:1], s[0:1], exec
	s_cselect_b32 s15, s19, s25
	s_cselect_b32 s21, s18, s24
	s_add_u32 s50, s24, 0x100
	s_addc_u32 s51, s25, 0
	s_mov_b32 s52, -2
	s_waitcnt lgkmcnt(0)
	s_add_u32 s0, s22, 0x100
	s_addc_u32 s1, s23, 0
	s_add_i32 s53, 0, 0x10000
	s_cmp_eq_u32 s52, 28
	s_cselect_b32 s27, s17, s1
	s_cselect_b32 s26, s16, s0
	s_cselect_b32 s25, s15, s51
	s_cselect_b32 s24, s21, s50
	s_add_i32 s54, 0, 0x14000
	v_add_u32_e32 v156, s53, v145
	v_add_u32_e32 v172, s54, v145
	ds_read_b128 v[140:143], v156
	ds_read_b128 v[148:151], v156 offset:1024
	ds_read_b128 v[152:155], v156 offset:2048
	ds_read_b128 v[156:159], v156 offset:3072
	ds_read_b128 v[160:163], v172
	ds_read_b128 v[164:167], v172 offset:1024
	ds_read_b128 v[168:171], v172 offset:2048
	ds_read_b128 v[172:175], v172 offset:3072
	s_add_i32 m0, s31, 0xc000
	ds_read_b128 v[176:179], v147
	ds_read_b128 v[180:183], v147 offset:1024
	ds_read_b128 v[184:187], v147 offset:2048
	ds_read_b128 v[208:211], v147 offset:3072
	ds_read_b128 v[230:233], v147 offset:4096
	ds_read_b128 v[234:237], v147 offset:5120
	ds_read_b128 v[238:241], v147 offset:6144
	ds_read_b128 v[242:245], v147 offset:7168
	global_load_lds_dwordx4 v138, s[22:23]
	s_add_i32 m0, s31, 0xe000
	s_nop 0
	global_load_lds_dwordx4 v136, s[22:23]
	s_waitcnt vmcnt(8)
	s_waitcnt lgkmcnt(0)
	s_barrier
	s_setprio 1
	s_waitcnt lgkmcnt(0)
	v_mfma_f32_16x16x32_bf16 v[126:129], v[140:143], v[176:179], 0
	v_mfma_f32_16x16x32_bf16 v[122:125], v[152:155], v[176:179], 0
	v_mfma_f32_16x16x32_bf16 v[108:111], v[140:143], v[184:187], 0
	v_mfma_f32_16x16x32_bf16 v[104:107], v[152:155], v[184:187], 0
	v_mfma_f32_16x16x32_bf16 v[92:95], v[140:143], v[230:233], 0
	v_mfma_f32_16x16x32_bf16 v[88:91], v[152:155], v[230:233], 0
	v_mfma_f32_16x16x32_bf16 v[76:79], v[140:143], v[238:241], 0
	v_mfma_f32_16x16x32_bf16 v[72:75], v[152:155], v[238:241], 0
	v_mfma_f32_16x16x32_bf16 v[126:129], v[148:151], v[180:183], v[126:129]
	v_mfma_f32_16x16x32_bf16 v[122:125], v[156:159], v[180:183], v[122:125]
	v_mfma_f32_16x16x32_bf16 v[108:111], v[148:151], v[208:211], v[108:111]
	v_mfma_f32_16x16x32_bf16 v[104:107], v[156:159], v[208:211], v[104:107]
	v_mfma_f32_16x16x32_bf16 v[92:95], v[148:151], v[234:237], v[92:95]
	v_mfma_f32_16x16x32_bf16 v[88:91], v[156:159], v[234:237], v[88:91]
	v_mfma_f32_16x16x32_bf16 v[76:79], v[148:151], v[242:245], v[76:79]
	v_mfma_f32_16x16x32_bf16 v[72:75], v[156:159], v[242:245], v[72:75]
	s_setprio 0
	s_setprio 1
	v_mfma_f32_16x16x32_bf16 v[118:121], v[160:163], v[176:179], 0
	v_mfma_f32_16x16x32_bf16 v[114:117], v[168:171], v[176:179], 0
	v_mfma_f32_16x16x32_bf16 v[100:103], v[160:163], v[184:187], 0
	v_mfma_f32_16x16x32_bf16 v[96:99], v[168:171], v[184:187], 0
	v_mfma_f32_16x16x32_bf16 v[84:87], v[160:163], v[230:233], 0
	v_mfma_f32_16x16x32_bf16 v[80:83], v[168:171], v[230:233], 0
	v_mfma_f32_16x16x32_bf16 v[68:71], v[160:163], v[238:241], 0
	v_mfma_f32_16x16x32_bf16 v[64:67], v[168:171], v[238:241], 0
	v_mfma_f32_16x16x32_bf16 v[118:121], v[164:167], v[180:183], v[118:121]
	v_mfma_f32_16x16x32_bf16 v[114:117], v[172:175], v[180:183], v[114:117]
	v_mfma_f32_16x16x32_bf16 v[100:103], v[164:167], v[208:211], v[100:103]
	v_mfma_f32_16x16x32_bf16 v[96:99], v[172:175], v[208:211], v[96:99]
	v_mfma_f32_16x16x32_bf16 v[84:87], v[164:167], v[234:237], v[84:87]
	v_mfma_f32_16x16x32_bf16 v[80:83], v[172:175], v[234:237], v[80:83]
	v_mfma_f32_16x16x32_bf16 v[68:71], v[164:167], v[242:245], v[68:71]
	v_mfma_f32_16x16x32_bf16 v[64:67], v[172:175], v[242:245], v[64:67]
	s_setprio 0
	s_barrier
	s_add_i32 s22, s53, s30
	s_mov_b32 m0, s22
	ds_read_b128 v[176:179], v147 offset:16384
	ds_read_b128 v[180:183], v147 offset:17408
	ds_read_b128 v[184:187], v147 offset:18432
	ds_read_b128 v[208:211], v147 offset:19456
	ds_read_b128 v[230:233], v147 offset:20480
	ds_read_b128 v[234:237], v147 offset:21504
	ds_read_b128 v[238:241], v147 offset:22528
	ds_read_b128 v[242:245], v147 offset:23552
	global_load_lds_dwordx4 v112, s[24:25]
	s_add_i32 m0, s22, 0x2000
	s_add_u32 s22, s24, 0x80000
	v_lshl_add_u64 v[212:213], s[24:25], 0, v[134:135]
	s_addc_u32 s23, s25, 0
	s_add_i32 s53, s54, s30
	global_load_lds_dwordx4 v134, s[24:25]
	s_mov_b32 m0, s53
	s_nop 0
	global_load_lds_dwordx4 v112, s[22:23]
	s_add_i32 m0, s53, 0x2000
	s_nop 0
	global_load_lds_dwordx4 v134, s[22:23]
	s_mov_b32 m0, s31
	s_nop 0
	global_load_lds_dwordx4 v130, s[26:27]
	s_mov_b32 m0, s35
	s_nop 0
	global_load_lds_dwordx4 v132, s[26:27]
	s_waitcnt vmcnt(8)
	s_waitcnt lgkmcnt(0)
	s_barrier
	s_setprio 1
	s_waitcnt lgkmcnt(0)
	v_mfma_f32_16x16x32_bf16 v[60:63], v[140:143], v[176:179], 0
	v_mfma_f32_16x16x32_bf16 v[56:59], v[152:155], v[176:179], 0
	v_mfma_f32_16x16x32_bf16 v[44:47], v[140:143], v[184:187], 0
	v_mfma_f32_16x16x32_bf16 v[40:43], v[152:155], v[184:187], 0
	v_mfma_f32_16x16x32_bf16 v[28:31], v[140:143], v[230:233], 0
	v_mfma_f32_16x16x32_bf16 v[24:27], v[152:155], v[230:233], 0
	v_mfma_f32_16x16x32_bf16 v[12:15], v[140:143], v[238:241], 0
	v_mfma_f32_16x16x32_bf16 v[8:11], v[152:155], v[238:241], 0
	v_mfma_f32_16x16x32_bf16 v[60:63], v[148:151], v[180:183], v[60:63]
	v_mfma_f32_16x16x32_bf16 v[56:59], v[156:159], v[180:183], v[56:59]
	v_mfma_f32_16x16x32_bf16 v[44:47], v[148:151], v[208:211], v[44:47]
	v_mfma_f32_16x16x32_bf16 v[40:43], v[156:159], v[208:211], v[40:43]
	v_mfma_f32_16x16x32_bf16 v[28:31], v[148:151], v[234:237], v[28:31]
	v_mfma_f32_16x16x32_bf16 v[24:27], v[156:159], v[234:237], v[24:27]
	v_mfma_f32_16x16x32_bf16 v[12:15], v[148:151], v[242:245], v[12:15]
	v_mfma_f32_16x16x32_bf16 v[8:11], v[156:159], v[242:245], v[8:11]
	s_setprio 0
	s_setprio 1
	v_mfma_f32_16x16x32_bf16 v[52:55], v[160:163], v[176:179], 0
	v_mfma_f32_16x16x32_bf16 v[48:51], v[168:171], v[176:179], 0
	v_mfma_f32_16x16x32_bf16 v[36:39], v[160:163], v[184:187], 0
	v_mfma_f32_16x16x32_bf16 v[32:35], v[168:171], v[184:187], 0
	v_mfma_f32_16x16x32_bf16 v[20:23], v[160:163], v[230:233], 0
	v_mfma_f32_16x16x32_bf16 v[16:19], v[168:171], v[230:233], 0
	v_mfma_f32_16x16x32_bf16 v[4:7], v[160:163], v[238:241], 0
	v_mfma_f32_16x16x32_bf16 v[0:3], v[168:171], v[238:241], 0
	v_mfma_f32_16x16x32_bf16 v[52:55], v[164:167], v[180:183], v[52:55]
	v_mfma_f32_16x16x32_bf16 v[48:51], v[172:175], v[180:183], v[48:51]
	v_mfma_f32_16x16x32_bf16 v[36:39], v[164:167], v[208:211], v[36:39]
	v_mfma_f32_16x16x32_bf16 v[32:35], v[172:175], v[208:211], v[32:35]
	v_mfma_f32_16x16x32_bf16 v[20:23], v[164:167], v[234:237], v[20:23]
	v_mfma_f32_16x16x32_bf16 v[16:19], v[172:175], v[234:237], v[16:19]
	v_mfma_f32_16x16x32_bf16 v[4:7], v[164:167], v[242:245], v[4:7]
	v_mfma_f32_16x16x32_bf16 v[0:3], v[172:175], v[242:245], v[0:3]
	s_setprio 0
	s_barrier
	s_add_i32 s53, 0, 0x18000
	s_add_i32 s54, 0, 0x1c000
	v_add_u32_e32 v156, s53, v145
	v_add_u32_e32 v172, s54, v145
	ds_read_b128 v[140:143], v156
	ds_read_b128 v[148:151], v156 offset:1024
	ds_read_b128 v[152:155], v156 offset:2048
	ds_read_b128 v[156:159], v156 offset:3072
	ds_read_b128 v[160:163], v172
	ds_read_b128 v[164:167], v172 offset:1024
	ds_read_b128 v[168:171], v172 offset:2048
	ds_read_b128 v[172:175], v172 offset:3072
	s_add_u32 s22, s26, 0x120000
	s_addc_u32 s23, s27, 0
	s_mov_b32 m0, s40
	ds_read_b128 v[176:179], v147 offset:32768
	ds_read_b128 v[180:183], v147 offset:33792
	ds_read_b128 v[184:187], v147 offset:34816
	ds_read_b128 v[208:211], v147 offset:35840
	ds_read_b128 v[230:233], v147 offset:36864
	ds_read_b128 v[234:237], v147 offset:37888
	ds_read_b128 v[238:241], v147 offset:38912
	ds_read_b128 v[242:245], v147 offset:39936
	global_load_lds_dwordx4 v130, s[22:23]
	s_mov_b32 m0, s41
	s_nop 0
	global_load_lds_dwordx4 v132, s[22:23]
	s_waitcnt vmcnt(8)
	s_waitcnt lgkmcnt(0)
	s_barrier
	s_setprio 1
	s_waitcnt lgkmcnt(0)
	v_mfma_f32_16x16x32_bf16 v[126:129], v[140:143], v[176:179], v[126:129]
	v_mfma_f32_16x16x32_bf16 v[122:125], v[152:155], v[176:179], v[122:125]
	v_mfma_f32_16x16x32_bf16 v[108:111], v[140:143], v[184:187], v[108:111]
	v_mfma_f32_16x16x32_bf16 v[104:107], v[152:155], v[184:187], v[104:107]
	v_mfma_f32_16x16x32_bf16 v[92:95], v[140:143], v[230:233], v[92:95]
	v_mfma_f32_16x16x32_bf16 v[88:91], v[152:155], v[230:233], v[88:91]
	v_mfma_f32_16x16x32_bf16 v[76:79], v[140:143], v[238:241], v[76:79]
	v_mfma_f32_16x16x32_bf16 v[72:75], v[152:155], v[238:241], v[72:75]
	v_mfma_f32_16x16x32_bf16 v[126:129], v[148:151], v[180:183], v[126:129]
	v_mfma_f32_16x16x32_bf16 v[122:125], v[156:159], v[180:183], v[122:125]
	v_mfma_f32_16x16x32_bf16 v[108:111], v[148:151], v[208:211], v[108:111]
	v_mfma_f32_16x16x32_bf16 v[104:107], v[156:159], v[208:211], v[104:107]
	v_mfma_f32_16x16x32_bf16 v[92:95], v[148:151], v[234:237], v[92:95]
	v_mfma_f32_16x16x32_bf16 v[88:91], v[156:159], v[234:237], v[88:91]
	v_mfma_f32_16x16x32_bf16 v[76:79], v[148:151], v[242:245], v[76:79]
	v_mfma_f32_16x16x32_bf16 v[72:75], v[156:159], v[242:245], v[72:75]
	s_setprio 0
	s_setprio 1
	v_mfma_f32_16x16x32_bf16 v[118:121], v[160:163], v[176:179], v[118:121]
	v_mfma_f32_16x16x32_bf16 v[114:117], v[168:171], v[176:179], v[114:117]
	v_mfma_f32_16x16x32_bf16 v[100:103], v[160:163], v[184:187], v[100:103]
	v_mfma_f32_16x16x32_bf16 v[96:99], v[168:171], v[184:187], v[96:99]
	v_mfma_f32_16x16x32_bf16 v[84:87], v[160:163], v[230:233], v[84:87]
	v_mfma_f32_16x16x32_bf16 v[80:83], v[168:171], v[230:233], v[80:83]
	v_mfma_f32_16x16x32_bf16 v[68:71], v[160:163], v[238:241], v[68:71]
	v_mfma_f32_16x16x32_bf16 v[64:67], v[168:171], v[238:241], v[64:67]
	v_mfma_f32_16x16x32_bf16 v[118:121], v[164:167], v[180:183], v[118:121]
	v_mfma_f32_16x16x32_bf16 v[114:117], v[172:175], v[180:183], v[114:117]
	v_mfma_f32_16x16x32_bf16 v[100:103], v[164:167], v[208:211], v[100:103]
	v_mfma_f32_16x16x32_bf16 v[96:99], v[172:175], v[208:211], v[96:99]
	v_mfma_f32_16x16x32_bf16 v[84:87], v[164:167], v[234:237], v[84:87]
	v_mfma_f32_16x16x32_bf16 v[80:83], v[172:175], v[234:237], v[80:83]
	v_mfma_f32_16x16x32_bf16 v[68:71], v[164:167], v[242:245], v[68:71]
	v_mfma_f32_16x16x32_bf16 v[64:67], v[172:175], v[242:245], v[64:67]
	s_setprio 0
	s_barrier
	s_add_i32 s22, s53, s30
	s_mov_b32 m0, s22
	ds_read_b128 v[176:179], v147 offset:49152
	ds_read_b128 v[180:183], v147 offset:50176
	ds_read_b128 v[184:187], v147 offset:51200
	ds_read_b128 v[208:211], v147 offset:52224
	ds_read_b128 v[230:233], v147 offset:53248
	ds_read_b128 v[234:237], v147 offset:54272
	ds_read_b128 v[238:241], v147 offset:55296
	ds_read_b128 v[242:245], v147 offset:56320
	s_add_u32 s98, s24, 0x80
	s_addc_u32 s99, s25, 0
	global_load_lds_dwordx4 v112, s[98:99]
	s_add_i32 m0, s22, 0x2000
	s_add_u32 s22, s24, 0x80080
	v_lshl_add_u64 v[188:189], v[212:213], 0, s[96:97]
	s_addc_u32 s23, s25, 0
	s_add_i32 s24, s54, s30
	global_load_lds_dwordx4 v[188:189], off
	s_mov_b32 m0, s24
	s_nop 0
	global_load_lds_dwordx4 v112, s[22:23]
	s_add_i32 m0, s24, 0x2000
	s_nop 0
	global_load_lds_dwordx4 v134, s[22:23]
	s_mov_b32 m0, s43
	s_nop 0
	s_add_u32 s98, s26, 0x80
	s_addc_u32 s99, s27, 0
	global_load_lds_dwordx4 v130, s[98:99]
	s_mov_b32 m0, s44
	s_nop 0
	s_add_u32 s98, s26, 0x80
	s_addc_u32 s99, s27, 0
	global_load_lds_dwordx4 v132, s[98:99]
	s_waitcnt vmcnt(8)
	s_waitcnt lgkmcnt(0)
	s_barrier
	s_setprio 1
	s_waitcnt lgkmcnt(0)
	v_mfma_f32_16x16x32_bf16 v[60:63], v[140:143], v[176:179], v[60:63]
	v_mfma_f32_16x16x32_bf16 v[56:59], v[152:155], v[176:179], v[56:59]
	v_mfma_f32_16x16x32_bf16 v[44:47], v[140:143], v[184:187], v[44:47]
	v_mfma_f32_16x16x32_bf16 v[40:43], v[152:155], v[184:187], v[40:43]
	v_mfma_f32_16x16x32_bf16 v[28:31], v[140:143], v[230:233], v[28:31]
	v_mfma_f32_16x16x32_bf16 v[24:27], v[152:155], v[230:233], v[24:27]
	v_mfma_f32_16x16x32_bf16 v[12:15], v[140:143], v[238:241], v[12:15]
	v_mfma_f32_16x16x32_bf16 v[8:11], v[152:155], v[238:241], v[8:11]
	v_mfma_f32_16x16x32_bf16 v[60:63], v[148:151], v[180:183], v[60:63]
	v_mfma_f32_16x16x32_bf16 v[56:59], v[156:159], v[180:183], v[56:59]
	v_mfma_f32_16x16x32_bf16 v[44:47], v[148:151], v[208:211], v[44:47]
	v_mfma_f32_16x16x32_bf16 v[40:43], v[156:159], v[208:211], v[40:43]
	v_mfma_f32_16x16x32_bf16 v[28:31], v[148:151], v[234:237], v[28:31]
	v_mfma_f32_16x16x32_bf16 v[24:27], v[156:159], v[234:237], v[24:27]
	v_mfma_f32_16x16x32_bf16 v[12:15], v[148:151], v[242:245], v[12:15]
	v_mfma_f32_16x16x32_bf16 v[8:11], v[156:159], v[242:245], v[8:11]
	s_setprio 0
	s_setprio 1
	v_mfma_f32_16x16x32_bf16 v[52:55], v[160:163], v[176:179], v[52:55]
	v_mfma_f32_16x16x32_bf16 v[48:51], v[168:171], v[176:179], v[48:51]
	v_mfma_f32_16x16x32_bf16 v[36:39], v[160:163], v[184:187], v[36:39]
	v_mfma_f32_16x16x32_bf16 v[32:35], v[168:171], v[184:187], v[32:35]
	v_mfma_f32_16x16x32_bf16 v[20:23], v[160:163], v[230:233], v[20:23]
	v_mfma_f32_16x16x32_bf16 v[16:19], v[168:171], v[230:233], v[16:19]
	v_mfma_f32_16x16x32_bf16 v[4:7], v[160:163], v[238:241], v[4:7]
	v_mfma_f32_16x16x32_bf16 v[0:3], v[168:171], v[238:241], v[0:3]
	v_mfma_f32_16x16x32_bf16 v[52:55], v[164:167], v[180:183], v[52:55]
	v_mfma_f32_16x16x32_bf16 v[48:51], v[172:175], v[180:183], v[48:51]
	v_mfma_f32_16x16x32_bf16 v[36:39], v[164:167], v[208:211], v[36:39]
	v_mfma_f32_16x16x32_bf16 v[32:35], v[172:175], v[208:211], v[32:35]
	v_mfma_f32_16x16x32_bf16 v[20:23], v[164:167], v[234:237], v[20:23]
	v_mfma_f32_16x16x32_bf16 v[16:19], v[172:175], v[234:237], v[16:19]
	v_mfma_f32_16x16x32_bf16 v[4:7], v[164:167], v[242:245], v[4:7]
	v_mfma_f32_16x16x32_bf16 v[0:3], v[172:175], v[242:245], v[0:3]
	s_setprio 0
	s_barrier
	s_add_i32 s52, s52, 2
	s_add_u32 s50, s50, 0x100
	s_addc_u32 s51, s51, 0
	s_cmp_gt_u32 s52, 29
	s_mov_b64 s[22:23], s[0:1]
	s_cbranch_scc0 .LBB0_804
	s_branch .Lpeel_exit_804
	.p2align 6

.LBB0_877:
	v_lshlrev_b32_e32 v32, 1, v208
	v_and_b32_e32 v236, 32, v32
	v_lshlrev_b32_e32 v32, 4, v208
	v_and_b32_e32 v32, 0xc0, v32
	v_lshl_or_b32 v234, v232, 8, v32
	v_add_u32_e32 v32, 0, v236
	v_add3_u32 v240, v32, v233, v234
	v_max3_f32 v32, v16, v17, v0
	v_max3_f32 v33, v18, v19, v1
	s_and_b32 s16, s53, 0xffffffc0
	v_max3_f32 v32, v32, v2, v3
	v_max3_f32 v33, v33, v22, v23
	s_and_b32 s20, s22, 0x3fffffc0
	v_max3_f32 v32, v32, v20, v21
	v_max3_f32 v33, v33, v6, v7
	s_add_i32 s92, s40, s16
	v_max3_f32 v32, v32, v4, v5
	v_max3_f32 v33, v33, v26, v27
	s_add_i32 s21, s23, 0x100
	v_max3_f32 v32, v32, v24, v25
	v_max3_f32 v33, v33, v10, v11
	s_lshl_b32 s20, s20, 2
	v_max3_f32 v32, v32, v8, v9
	v_max3_f32 v33, v33, v30, v31
	s_lshl_b64 s[16:17], s[92:93], 1
	v_max3_f32 v32, v32, v28, v29
	v_max3_f32 v33, v33, v14, v15
	s_add_i32 s57, s20, 0
	v_max3_f32 v32, v32, v12, v13
	s_lshr_b32 s59, s21, 6
	v_max_f32_e32 v32, v32, v33
	s_mov_b64 s[20:21], 0x60000
	v_mov_b32_e32 v33, v32
	s_nop 1
	v_permlane32_swap_b32_e32 v32, v33
	v_max_f32_e32 v32, v32, v33
	s_cmp_lg_u32 0, -1
	v_add_f32_e32 v238, v113, v32
	v_sub_f32_e32 v16, v16, v32
	v_sub_f32_e32 v0, v0, v32
	v_sub_f32_e32 v17, v17, v32
	v_sub_f32_e32 v1, v1, v32
	v_sub_f32_e32 v18, v18, v32
	v_sub_f32_e32 v2, v2, v32
	v_sub_f32_e32 v19, v19, v32
	v_sub_f32_e32 v3, v3, v32
	v_sub_f32_e32 v20, v20, v32
	v_sub_f32_e32 v4, v4, v32
	v_sub_f32_e32 v21, v21, v32
	v_sub_f32_e32 v5, v5, v32
	v_sub_f32_e32 v22, v22, v32
	v_sub_f32_e32 v6, v6, v32
	v_sub_f32_e32 v23, v23, v32
	v_sub_f32_e32 v7, v7, v32
	v_sub_f32_e32 v24, v24, v32
	v_sub_f32_e32 v8, v8, v32
	v_sub_f32_e32 v25, v25, v32
	v_sub_f32_e32 v9, v9, v32
	v_sub_f32_e32 v26, v26, v32
	v_sub_f32_e32 v10, v10, v32
	v_sub_f32_e32 v27, v27, v32
	v_sub_f32_e32 v11, v11, v32
	v_sub_f32_e32 v28, v28, v32
	v_sub_f32_e32 v12, v12, v32
	v_sub_f32_e32 v29, v29, v32
	v_sub_f32_e32 v13, v13, v32
	v_sub_f32_e32 v30, v30, v32
	v_sub_f32_e32 v14, v14, v32
	v_sub_f32_e32 v31, v31, v32
	v_sub_f32_e32 v15, v15, v32
	s_nop 0
	v_xor_b32_e32 v32, 0x80000000, v238
	v_mov_b32_e32 v33, v32
	v_mov_b32_e32 v34, v32
	v_mov_b32_e32 v35, v32
	v_mov_b32_e32 v36, v32
	v_mov_b32_e32 v37, v32
	v_mov_b32_e32 v38, v32
	v_mov_b32_e32 v39, v32
	v_mov_b32_e32 v40, v32
	v_mov_b32_e32 v41, v32
	v_mov_b32_e32 v42, v32
	v_mov_b32_e32 v43, v32
	v_mov_b32_e32 v44, v32
	v_mov_b32_e32 v45, v32
	v_mov_b32_e32 v46, v32
	v_mov_b32_e32 v47, v32
	s_waitcnt vmcnt(0) lgkmcnt(0)
	s_barrier
	v_exp_f32_e32 v48, v0
	v_exp_f32_e32 v49, v1
	v_lshl_add_u64 v[0:1], v[80:81], 0, s[20:21]
	s_mov_b32 s20, m0
	s_mov_b32 m0, s35
	s_nop 0
	global_load_lds_dwordx4 v[0:1], off
	s_mov_b32 m0, s20
	s_cselect_b32 s20, 0, 0
	s_add_i32 s19, s20, s19
	v_lshl_add_u64 v[0:1], v[82:83], 0, s[78:79]
	s_add_i32 s19, s19, 0x8000
	s_mov_b32 s20, m0
	s_mov_b32 m0, s19
	s_nop 0
	global_load_lds_dwordx4 v[0:1], off
	s_mov_b32 m0, s20
	ds_read_b128 v[174:177], v239 offset:8192
	ds_read_b128 v[170:173], v239 offset:8704
	ds_read_b128 v[166:169], v239 offset:10240
	ds_read_b128 v[162:165], v239 offset:10752
	ds_read_b128 v[158:161], v239 offset:12288
	ds_read_b128 v[154:157], v239 offset:12800
	ds_read_b128 v[150:153], v239 offset:14336
	ds_read_b128 v[146:149], v239 offset:14848
	v_exp_f32_e32 v64, v16
	v_exp_f32_e32 v65, v17
	v_exp_f32_e32 v66, v18
	v_exp_f32_e32 v67, v19
	v_exp_f32_e32 v68, v20
	v_exp_f32_e32 v69, v21
	v_exp_f32_e32 v70, v22
	v_exp_f32_e32 v71, v23
	v_exp_f32_e32 v72, v24
	v_exp_f32_e32 v73, v25
	v_exp_f32_e32 v74, v26
	v_exp_f32_e32 v75, v27
	v_exp_f32_e32 v76, v28
	v_exp_f32_e32 v77, v29
	v_exp_f32_e32 v78, v30
	v_exp_f32_e32 v79, v31
	v_exp_f32_e32 v50, v2
	v_exp_f32_e32 v51, v3
	v_exp_f32_e32 v52, v4
	v_exp_f32_e32 v53, v5
	v_exp_f32_e32 v54, v6
	v_exp_f32_e32 v55, v7
	v_exp_f32_e32 v56, v8
	v_exp_f32_e32 v57, v9
	v_exp_f32_e32 v58, v10
	v_exp_f32_e32 v59, v11
	v_exp_f32_e32 v60, v12
	v_exp_f32_e32 v61, v13
	v_exp_f32_e32 v62, v14
	v_exp_f32_e32 v63, v15
	s_waitcnt vmcnt(2) lgkmcnt(0)
	s_barrier
	s_mov_b32 s18, 1
	s_mov_b32 s62, 0
	s_andn2_b64 vcc, exec, s[2:3]
	v_cmp_gt_u32_e64 s[2:3], 32, v195
	s_cbranch_vccnz .LBB0_893
	v_and_b32_e32 v0, 3, v208
	s_lshl_b32 s18, s22, 9
	v_lshlrev_b32_e32 v0, 4, v0
	v_mov_b32_e32 v1, v113
	s_and_b32 s18, s18, 0x18000
	v_lshl_add_u64 v[0:1], s[14:15], 1, v[0:1]
	v_lshl_or_b32 v2, v209, 11, s18
	v_mov_b32_e32 v3, v113
	s_add_u32 s18, s4, s16
	v_lshl_add_u64 v[0:1], v[0:1], 0, v[2:3]
	s_addc_u32 s19, s5, s17
	v_lshl_add_u64 v[182:183], s[18:19], 0, v[0:1]
	s_lshl_b64 s[18:19], s[0:1], 1
	v_lshlrev_b32_e32 v4, 4, v232
	s_add_u32 s18, s47, s18
	v_mov_b32_e32 v16, v113
	v_mov_b32_e32 v17, v113
	s_addc_u32 s19, s48, s19
	v_mov_b32_e32 v18, v113
	v_mov_b32_e32 v19, v113
	v_mov_b32_e32 v20, v113
	v_mov_b32_e32 v21, v113
	v_mov_b32_e32 v22, v113
	v_mov_b32_e32 v23, v113
	v_mov_b32_e32 v24, v113
	v_mov_b32_e32 v25, v113
	v_mov_b32_e32 v26, v113
	v_mov_b32_e32 v27, v113
	v_mov_b32_e32 v28, v113
	v_mov_b32_e32 v29, v113
	v_mov_b32_e32 v30, v113
	v_mov_b32_e32 v31, v113
	v_add_u32_e32 v211, s57, v4
	v_mov_b64_e32 v[0:1], v[16:17]
	v_lshl_add_u32 v210, v231, 2, s57
	v_lshl_add_u64 v[184:185], s[18:19], 0, v[112:113]
	s_mov_b32 s18, 0
	s_movk_i32 s62, 0x4000
	s_movk_i32 s64, 0x2000
	v_mov_b32_e32 v241, 0
	s_mov_b32 s63, 6
	v_mov_b64_e32 v[2:3], v[18:19]
	v_mov_b64_e32 v[4:5], v[20:21]
	v_mov_b64_e32 v[6:7], v[22:23]
	v_mov_b64_e32 v[8:9], v[24:25]
	v_mov_b64_e32 v[10:11], v[26:27]
	v_mov_b64_e32 v[12:13], v[28:29]
	v_mov_b64_e32 v[14:15], v[30:31]
	.p2align 6

.LBB0_901:
	s_lshl_b32 s19, s18, 6
	s_addk_i32 s19, 0x7b
	v_add_u32_e32 v80, s19, v235
	v_subrev_u32_e32 v243, s23, v80
	v_and_b32_e32 v80, 3, v208
	v_lshlrev_b32_e32 v80, 4, v80
	v_mov_b32_e32 v81, v113
	s_mov_b32 s19, s93
	v_lshl_add_u64 v[80:81], s[14:15], 1, v[80:81]
	s_lshl_b32 s14, s22, 9
	s_sub_i32 s63, 0, s59
	s_add_i32 s20, s18, 2
	s_lshl_b64 s[18:19], s[18:19], 17
	s_and_b32 s14, s14, 0x18000
	v_lshl_or_b32 v82, v209, 11, s14
	s_add_u32 s14, s49, s16
	s_addc_u32 s15, s50, s17
	s_lshl_b64 s[0:1], s[0:1], 1
	v_mov_b32_e32 v83, v113
	s_add_u32 s0, s51, s0
	v_lshlrev_b32_e32 v84, 4, v232
	v_lshl_add_u64 v[80:81], v[80:81], 0, v[82:83]
	s_addc_u32 s1, s52, s1
	v_cmp_gt_u32_e64 s[2:3], 32, v195
	v_lshl_add_u32 v242, v231, 2, s57
	v_lshl_add_u64 v[208:209], s[14:15], 0, v[80:81]
	v_lshl_add_u64 v[210:211], s[0:1], 0, v[112:113]
	v_add_u32_e32 v112, s57, v84
	.p2align 6

.LBB0_1136:
	s_add_u32 s48, s18, 0x100
	s_addc_u32 s49, s19, 0
	s_mov_b32 s50, -2
	s_waitcnt lgkmcnt(0)
	s_add_u32 s18, s16, 0x100
	s_addc_u32 s19, s17, 0
	s_add_i32 s51, 0, 0x10000
	s_cmp_eq_u32 s50, 40
	s_cselect_b32 s23, s1, s19
	s_cselect_b32 s22, s0, s18
	s_cselect_b32 s21, s15, s49
	s_cselect_b32 s20, s14, s48
	s_add_i32 s52, 0, 0x14000
	v_add_u32_e32 v156, s51, v145
	v_add_u32_e32 v172, s52, v145
	ds_read_b128 v[140:143], v156
	ds_read_b128 v[148:151], v156 offset:1024
	ds_read_b128 v[152:155], v156 offset:2048
	ds_read_b128 v[156:159], v156 offset:3072
	ds_read_b128 v[160:163], v172
	ds_read_b128 v[164:167], v172 offset:1024
	ds_read_b128 v[168:171], v172 offset:2048
	ds_read_b128 v[172:175], v172 offset:3072
	s_add_i32 m0, s31, 0xc000
	ds_read_b128 v[176:179], v147
	ds_read_b128 v[180:183], v147 offset:1024
	ds_read_b128 v[184:187], v147 offset:2048
	ds_read_b128 v[208:211], v147 offset:3072
	ds_read_b128 v[230:233], v147 offset:4096
	ds_read_b128 v[234:237], v147 offset:5120
	ds_read_b128 v[238:241], v147 offset:6144
	ds_read_b128 v[242:245], v147 offset:7168
	global_load_lds_dwordx4 v138, s[16:17]
	s_add_i32 m0, s31, 0xe000
	s_nop 0
	global_load_lds_dwordx4 v136, s[16:17]
	s_waitcnt vmcnt(8)
	s_waitcnt lgkmcnt(0)
	s_barrier
	s_setprio 1
	s_waitcnt lgkmcnt(0)
	v_mfma_f32_16x16x32_bf16 v[126:129], v[140:143], v[176:179], 0
	v_mfma_f32_16x16x32_bf16 v[122:125], v[152:155], v[176:179], 0
	v_mfma_f32_16x16x32_bf16 v[108:111], v[140:143], v[184:187], 0
	v_mfma_f32_16x16x32_bf16 v[104:107], v[152:155], v[184:187], 0
	v_mfma_f32_16x16x32_bf16 v[92:95], v[140:143], v[230:233], 0
	v_mfma_f32_16x16x32_bf16 v[88:91], v[152:155], v[230:233], 0
	v_mfma_f32_16x16x32_bf16 v[76:79], v[140:143], v[238:241], 0
	v_mfma_f32_16x16x32_bf16 v[72:75], v[152:155], v[238:241], 0
	v_mfma_f32_16x16x32_bf16 v[126:129], v[148:151], v[180:183], v[126:129]
	v_mfma_f32_16x16x32_bf16 v[122:125], v[156:159], v[180:183], v[122:125]
	v_mfma_f32_16x16x32_bf16 v[108:111], v[148:151], v[208:211], v[108:111]
	v_mfma_f32_16x16x32_bf16 v[104:107], v[156:159], v[208:211], v[104:107]
	v_mfma_f32_16x16x32_bf16 v[92:95], v[148:151], v[234:237], v[92:95]
	v_mfma_f32_16x16x32_bf16 v[88:91], v[156:159], v[234:237], v[88:91]
	v_mfma_f32_16x16x32_bf16 v[76:79], v[148:151], v[242:245], v[76:79]
	v_mfma_f32_16x16x32_bf16 v[72:75], v[156:159], v[242:245], v[72:75]
	s_setprio 0
	s_setprio 1
	v_mfma_f32_16x16x32_bf16 v[118:121], v[160:163], v[176:179], 0
	v_mfma_f32_16x16x32_bf16 v[114:117], v[168:171], v[176:179], 0
	v_mfma_f32_16x16x32_bf16 v[100:103], v[160:163], v[184:187], 0
	v_mfma_f32_16x16x32_bf16 v[96:99], v[168:171], v[184:187], 0
	v_mfma_f32_16x16x32_bf16 v[84:87], v[160:163], v[230:233], 0
	v_mfma_f32_16x16x32_bf16 v[80:83], v[168:171], v[230:233], 0
	v_mfma_f32_16x16x32_bf16 v[68:71], v[160:163], v[238:241], 0
	v_mfma_f32_16x16x32_bf16 v[64:67], v[168:171], v[238:241], 0
	v_mfma_f32_16x16x32_bf16 v[118:121], v[164:167], v[180:183], v[118:121]
	v_mfma_f32_16x16x32_bf16 v[114:117], v[172:175], v[180:183], v[114:117]
	v_mfma_f32_16x16x32_bf16 v[100:103], v[164:167], v[208:211], v[100:103]
	v_mfma_f32_16x16x32_bf16 v[96:99], v[172:175], v[208:211], v[96:99]
	v_mfma_f32_16x16x32_bf16 v[84:87], v[164:167], v[234:237], v[84:87]
	v_mfma_f32_16x16x32_bf16 v[80:83], v[172:175], v[234:237], v[80:83]
	v_mfma_f32_16x16x32_bf16 v[68:71], v[164:167], v[242:245], v[68:71]
	v_mfma_f32_16x16x32_bf16 v[64:67], v[172:175], v[242:245], v[64:67]
	s_setprio 0
	s_barrier
	s_add_i32 s16, s51, s30
	s_mov_b32 m0, s16
	ds_read_b128 v[176:179], v147 offset:16384
	ds_read_b128 v[180:183], v147 offset:17408
	ds_read_b128 v[184:187], v147 offset:18432
	ds_read_b128 v[208:211], v147 offset:19456
	ds_read_b128 v[230:233], v147 offset:20480
	ds_read_b128 v[234:237], v147 offset:21504
	ds_read_b128 v[238:241], v147 offset:22528
	ds_read_b128 v[242:245], v147 offset:23552
	global_load_lds_dwordx4 v112, s[20:21]
	s_add_i32 m0, s16, 0x2000
	s_add_u32 s16, s20, 0xb0000
	v_lshl_add_u64 v[212:213], s[20:21], 0, v[134:135]
	s_addc_u32 s17, s21, 0
	s_add_i32 s51, s52, s30
	global_load_lds_dwordx4 v134, s[20:21]
	s_mov_b32 m0, s51
	s_nop 0
	global_load_lds_dwordx4 v112, s[16:17]
	s_add_i32 m0, s51, 0x2000
	s_nop 0
	global_load_lds_dwordx4 v134, s[16:17]
	s_mov_b32 m0, s31
	s_nop 0
	global_load_lds_dwordx4 v130, s[22:23]
	s_mov_b32 m0, s35
	s_nop 0
	global_load_lds_dwordx4 v132, s[22:23]
	s_waitcnt vmcnt(8)
	s_waitcnt lgkmcnt(0)
	s_barrier
	s_setprio 1
	s_waitcnt lgkmcnt(0)
	v_mfma_f32_16x16x32_bf16 v[60:63], v[140:143], v[176:179], 0
	v_mfma_f32_16x16x32_bf16 v[56:59], v[152:155], v[176:179], 0
	v_mfma_f32_16x16x32_bf16 v[44:47], v[140:143], v[184:187], 0
	v_mfma_f32_16x16x32_bf16 v[40:43], v[152:155], v[184:187], 0
	v_mfma_f32_16x16x32_bf16 v[28:31], v[140:143], v[230:233], 0
	v_mfma_f32_16x16x32_bf16 v[24:27], v[152:155], v[230:233], 0
	v_mfma_f32_16x16x32_bf16 v[12:15], v[140:143], v[238:241], 0
	v_mfma_f32_16x16x32_bf16 v[8:11], v[152:155], v[238:241], 0
	v_mfma_f32_16x16x32_bf16 v[60:63], v[148:151], v[180:183], v[60:63]
	v_mfma_f32_16x16x32_bf16 v[56:59], v[156:159], v[180:183], v[56:59]
	v_mfma_f32_16x16x32_bf16 v[44:47], v[148:151], v[208:211], v[44:47]
	v_mfma_f32_16x16x32_bf16 v[40:43], v[156:159], v[208:211], v[40:43]
	v_mfma_f32_16x16x32_bf16 v[28:31], v[148:151], v[234:237], v[28:31]
	v_mfma_f32_16x16x32_bf16 v[24:27], v[156:159], v[234:237], v[24:27]
	v_mfma_f32_16x16x32_bf16 v[12:15], v[148:151], v[242:245], v[12:15]
	v_mfma_f32_16x16x32_bf16 v[8:11], v[156:159], v[242:245], v[8:11]
	s_setprio 0
	s_setprio 1
	v_mfma_f32_16x16x32_bf16 v[52:55], v[160:163], v[176:179], 0
	v_mfma_f32_16x16x32_bf16 v[48:51], v[168:171], v[176:179], 0
	v_mfma_f32_16x16x32_bf16 v[36:39], v[160:163], v[184:187], 0
	v_mfma_f32_16x16x32_bf16 v[32:35], v[168:171], v[184:187], 0
	v_mfma_f32_16x16x32_bf16 v[20:23], v[160:163], v[230:233], 0
	v_mfma_f32_16x16x32_bf16 v[16:19], v[168:171], v[230:233], 0
	v_mfma_f32_16x16x32_bf16 v[4:7], v[160:163], v[238:241], 0
	v_mfma_f32_16x16x32_bf16 v[0:3], v[168:171], v[238:241], 0
	v_mfma_f32_16x16x32_bf16 v[52:55], v[164:167], v[180:183], v[52:55]
	v_mfma_f32_16x16x32_bf16 v[48:51], v[172:175], v[180:183], v[48:51]
	v_mfma_f32_16x16x32_bf16 v[36:39], v[164:167], v[208:211], v[36:39]
	v_mfma_f32_16x16x32_bf16 v[32:35], v[172:175], v[208:211], v[32:35]
	v_mfma_f32_16x16x32_bf16 v[20:23], v[164:167], v[234:237], v[20:23]
	v_mfma_f32_16x16x32_bf16 v[16:19], v[172:175], v[234:237], v[16:19]
	v_mfma_f32_16x16x32_bf16 v[4:7], v[164:167], v[242:245], v[4:7]
	v_mfma_f32_16x16x32_bf16 v[0:3], v[172:175], v[242:245], v[0:3]
	s_setprio 0
	s_barrier
	s_add_i32 s51, 0, 0x18000
	s_add_i32 s52, 0, 0x1c000
	v_add_u32_e32 v156, s51, v145
	v_add_u32_e32 v172, s52, v145
	ds_read_b128 v[140:143], v156
	ds_read_b128 v[148:151], v156 offset:1024
	ds_read_b128 v[152:155], v156 offset:2048
	ds_read_b128 v[156:159], v156 offset:3072
	ds_read_b128 v[160:163], v172
	ds_read_b128 v[164:167], v172 offset:1024
	ds_read_b128 v[168:171], v172 offset:2048
	ds_read_b128 v[172:175], v172 offset:3072
	s_add_u32 s16, s22, 0xb0000
	s_addc_u32 s17, s23, 0
	s_mov_b32 m0, s36
	ds_read_b128 v[176:179], v147 offset:32768
	ds_read_b128 v[180:183], v147 offset:33792
	ds_read_b128 v[184:187], v147 offset:34816
	ds_read_b128 v[208:211], v147 offset:35840
	ds_read_b128 v[230:233], v147 offset:36864
	ds_read_b128 v[234:237], v147 offset:37888
	ds_read_b128 v[238:241], v147 offset:38912
	ds_read_b128 v[242:245], v147 offset:39936
	global_load_lds_dwordx4 v130, s[16:17]
	s_mov_b32 m0, s37
	s_nop 0
	global_load_lds_dwordx4 v132, s[16:17]
	s_waitcnt vmcnt(8)
	s_waitcnt lgkmcnt(0)
	s_barrier
	s_setprio 1
	s_waitcnt lgkmcnt(0)
	v_mfma_f32_16x16x32_bf16 v[126:129], v[140:143], v[176:179], v[126:129]
	v_mfma_f32_16x16x32_bf16 v[122:125], v[152:155], v[176:179], v[122:125]
	v_mfma_f32_16x16x32_bf16 v[108:111], v[140:143], v[184:187], v[108:111]
	v_mfma_f32_16x16x32_bf16 v[104:107], v[152:155], v[184:187], v[104:107]
	v_mfma_f32_16x16x32_bf16 v[92:95], v[140:143], v[230:233], v[92:95]
	v_mfma_f32_16x16x32_bf16 v[88:91], v[152:155], v[230:233], v[88:91]
	v_mfma_f32_16x16x32_bf16 v[76:79], v[140:143], v[238:241], v[76:79]
	v_mfma_f32_16x16x32_bf16 v[72:75], v[152:155], v[238:241], v[72:75]
	v_mfma_f32_16x16x32_bf16 v[126:129], v[148:151], v[180:183], v[126:129]
	v_mfma_f32_16x16x32_bf16 v[122:125], v[156:159], v[180:183], v[122:125]
	v_mfma_f32_16x16x32_bf16 v[108:111], v[148:151], v[208:211], v[108:111]
	v_mfma_f32_16x16x32_bf16 v[104:107], v[156:159], v[208:211], v[104:107]
	v_mfma_f32_16x16x32_bf16 v[92:95], v[148:151], v[234:237], v[92:95]
	v_mfma_f32_16x16x32_bf16 v[88:91], v[156:159], v[234:237], v[88:91]
	v_mfma_f32_16x16x32_bf16 v[76:79], v[148:151], v[242:245], v[76:79]
	v_mfma_f32_16x16x32_bf16 v[72:75], v[156:159], v[242:245], v[72:75]
	s_setprio 0
	s_setprio 1
	v_mfma_f32_16x16x32_bf16 v[118:121], v[160:163], v[176:179], v[118:121]
	v_mfma_f32_16x16x32_bf16 v[114:117], v[168:171], v[176:179], v[114:117]
	v_mfma_f32_16x16x32_bf16 v[100:103], v[160:163], v[184:187], v[100:103]
	v_mfma_f32_16x16x32_bf16 v[96:99], v[168:171], v[184:187], v[96:99]
	v_mfma_f32_16x16x32_bf16 v[84:87], v[160:163], v[230:233], v[84:87]
	v_mfma_f32_16x16x32_bf16 v[80:83], v[168:171], v[230:233], v[80:83]
	v_mfma_f32_16x16x32_bf16 v[68:71], v[160:163], v[238:241], v[68:71]
	v_mfma_f32_16x16x32_bf16 v[64:67], v[168:171], v[238:241], v[64:67]
	v_mfma_f32_16x16x32_bf16 v[118:121], v[164:167], v[180:183], v[118:121]
	v_mfma_f32_16x16x32_bf16 v[114:117], v[172:175], v[180:183], v[114:117]
	v_mfma_f32_16x16x32_bf16 v[100:103], v[164:167], v[208:211], v[100:103]
	v_mfma_f32_16x16x32_bf16 v[96:99], v[172:175], v[208:211], v[96:99]
	v_mfma_f32_16x16x32_bf16 v[84:87], v[164:167], v[234:237], v[84:87]
	v_mfma_f32_16x16x32_bf16 v[80:83], v[172:175], v[234:237], v[80:83]
	v_mfma_f32_16x16x32_bf16 v[68:71], v[164:167], v[242:245], v[68:71]
	v_mfma_f32_16x16x32_bf16 v[64:67], v[172:175], v[242:245], v[64:67]
	s_setprio 0
	s_barrier
	s_add_i32 s16, s51, s30
	s_mov_b32 m0, s16
	ds_read_b128 v[176:179], v147 offset:49152
	ds_read_b128 v[180:183], v147 offset:50176
	ds_read_b128 v[184:187], v147 offset:51200
	ds_read_b128 v[208:211], v147 offset:52224
	ds_read_b128 v[230:233], v147 offset:53248
	ds_read_b128 v[234:237], v147 offset:54272
	ds_read_b128 v[238:241], v147 offset:55296
	ds_read_b128 v[242:245], v147 offset:56320
	s_add_u32 s98, s20, 0x80
	s_addc_u32 s99, s21, 0
	global_load_lds_dwordx4 v112, s[98:99]
	s_add_i32 m0, s16, 0x2000
	s_add_u32 s16, s20, 0xb0080
	v_lshl_add_u64 v[188:189], v[212:213], 0, s[96:97]
	s_addc_u32 s17, s21, 0
	s_add_i32 s20, s52, s30
	global_load_lds_dwordx4 v[188:189], off
	s_mov_b32 m0, s20
	s_nop 0
	global_load_lds_dwordx4 v112, s[16:17]
	s_add_i32 m0, s20, 0x2000
	s_nop 0
	global_load_lds_dwordx4 v134, s[16:17]
	s_mov_b32 m0, s39
	s_nop 0
	s_add_u32 s98, s22, 0x80
	s_addc_u32 s99, s23, 0
	global_load_lds_dwordx4 v130, s[98:99]
	s_mov_b32 m0, s40
	s_nop 0
	s_add_u32 s98, s22, 0x80
	s_addc_u32 s99, s23, 0
	global_load_lds_dwordx4 v132, s[98:99]
	s_waitcnt vmcnt(8)
	s_waitcnt lgkmcnt(0)
	s_barrier
	s_setprio 1
	s_waitcnt lgkmcnt(0)
	v_mfma_f32_16x16x32_bf16 v[60:63], v[140:143], v[176:179], v[60:63]
	v_mfma_f32_16x16x32_bf16 v[56:59], v[152:155], v[176:179], v[56:59]
	v_mfma_f32_16x16x32_bf16 v[44:47], v[140:143], v[184:187], v[44:47]
	v_mfma_f32_16x16x32_bf16 v[40:43], v[152:155], v[184:187], v[40:43]
	v_mfma_f32_16x16x32_bf16 v[28:31], v[140:143], v[230:233], v[28:31]
	v_mfma_f32_16x16x32_bf16 v[24:27], v[152:155], v[230:233], v[24:27]
	v_mfma_f32_16x16x32_bf16 v[12:15], v[140:143], v[238:241], v[12:15]
	v_mfma_f32_16x16x32_bf16 v[8:11], v[152:155], v[238:241], v[8:11]
	v_mfma_f32_16x16x32_bf16 v[60:63], v[148:151], v[180:183], v[60:63]
	v_mfma_f32_16x16x32_bf16 v[56:59], v[156:159], v[180:183], v[56:59]
	v_mfma_f32_16x16x32_bf16 v[44:47], v[148:151], v[208:211], v[44:47]
	v_mfma_f32_16x16x32_bf16 v[40:43], v[156:159], v[208:211], v[40:43]
	v_mfma_f32_16x16x32_bf16 v[28:31], v[148:151], v[234:237], v[28:31]
	v_mfma_f32_16x16x32_bf16 v[24:27], v[156:159], v[234:237], v[24:27]
	v_mfma_f32_16x16x32_bf16 v[12:15], v[148:151], v[242:245], v[12:15]
	v_mfma_f32_16x16x32_bf16 v[8:11], v[156:159], v[242:245], v[8:11]
	s_setprio 0
	s_setprio 1
	v_mfma_f32_16x16x32_bf16 v[52:55], v[160:163], v[176:179], v[52:55]
	v_mfma_f32_16x16x32_bf16 v[48:51], v[168:171], v[176:179], v[48:51]
	v_mfma_f32_16x16x32_bf16 v[36:39], v[160:163], v[184:187], v[36:39]
	v_mfma_f32_16x16x32_bf16 v[32:35], v[168:171], v[184:187], v[32:35]
	v_mfma_f32_16x16x32_bf16 v[20:23], v[160:163], v[230:233], v[20:23]
	v_mfma_f32_16x16x32_bf16 v[16:19], v[168:171], v[230:233], v[16:19]
	v_mfma_f32_16x16x32_bf16 v[4:7], v[160:163], v[238:241], v[4:7]
	v_mfma_f32_16x16x32_bf16 v[0:3], v[168:171], v[238:241], v[0:3]
	v_mfma_f32_16x16x32_bf16 v[52:55], v[164:167], v[180:183], v[52:55]
	v_mfma_f32_16x16x32_bf16 v[48:51], v[172:175], v[180:183], v[48:51]
	v_mfma_f32_16x16x32_bf16 v[36:39], v[164:167], v[208:211], v[36:39]
	v_mfma_f32_16x16x32_bf16 v[32:35], v[172:175], v[208:211], v[32:35]
	v_mfma_f32_16x16x32_bf16 v[20:23], v[164:167], v[234:237], v[20:23]
	v_mfma_f32_16x16x32_bf16 v[16:19], v[172:175], v[234:237], v[16:19]
	v_mfma_f32_16x16x32_bf16 v[4:7], v[164:167], v[242:245], v[4:7]
	v_mfma_f32_16x16x32_bf16 v[0:3], v[172:175], v[242:245], v[0:3]
	s_setprio 0
	s_barrier
	s_add_i32 s50, s50, 2
	s_add_u32 s48, s48, 0x100
	s_addc_u32 s49, s49, 0
	s_cmp_gt_u32 s50, 41
	s_mov_b64 s[16:17], s[18:19]
	s_cbranch_scc0 .LBB0_1137
	s_branch .Lpeel_exit_1137
	.p2align 6

.LBB0_1951:
	s_ashr_i32 s17, s16, 31
	s_lshl_b64 s[18:19], s[16:17], 19
	s_add_u32 s18, s42, s18
	s_addc_u32 s19, s43, s19
	s_and_b64 s[20:21], s[2:3], exec
	s_cselect_b32 s5, s19, s27
	s_cselect_b32 s17, s18, s26
	s_ashr_i32 s15, s14, 31
	s_lshl_b64 s[20:21], s[14:15], 19
	s_add_u32 s20, s40, s20
	s_addc_u32 s21, s41, s21
	s_and_b64 s[28:29], s[2:3], exec
	s_cselect_b32 s15, s21, s25
	s_cselect_b32 s51, s20, s24
	s_add_u32 s52, s24, 0x100
	s_addc_u32 s53, s25, 0
	s_add_u32 s24, s26, 0x40080
	s_addc_u32 s25, s27, 0
	s_mov_b32 s54, -2
	s_add_u32 s26, s24, 0xfffc0080
	s_addc_u32 s27, s25, -1
	s_add_i32 s55, 0, 0x10000
	s_cmp_eq_u32 s54, 12
	s_cselect_b32 s29, s5, s27
	s_cselect_b32 s28, s17, s26
	v_add_u32_e32 v144, s55, v146
	s_cselect_b32 s27, s15, s53
	s_cselect_b32 s26, s51, s52
	s_add_i32 s58, 0, 0x14000
	ds_read_b128 v[140:143], v144
	ds_read_b128 v[150:153], v144 offset:1024
	ds_read_b128 v[154:157], v144 offset:2048
	ds_read_b128 v[158:161], v144 offset:3072
	v_add_u32_e32 v144, s58, v146
	ds_read_b128 v[162:165], v144
	ds_read_b128 v[166:169], v144 offset:1024
	ds_read_b128 v[170:173], v144 offset:2048
	ds_read_b128 v[174:177], v144 offset:3072
	s_add_i32 m0, s23, 0xc000
	ds_read_b128 v[178:181], v149
	ds_read_b128 v[182:185], v149 offset:1024
	ds_read_b128 v[186:189], v149 offset:2048
	ds_read_b128 v[208:211], v149 offset:3072
	ds_read_b128 v[230:233], v149 offset:4096
	ds_read_b128 v[234:237], v149 offset:5120
	ds_read_b128 v[238:241], v149 offset:6144
	ds_read_b128 v[242:245], v149 offset:7168
	global_load_lds_dwordx4 v138, s[24:25]
	s_add_i32 m0, s23, 0xe000
	s_nop 0
	global_load_lds_dwordx4 v136, s[24:25]
	s_waitcnt vmcnt(8)
	s_waitcnt lgkmcnt(0)
	s_barrier
	s_setprio 1
	s_waitcnt lgkmcnt(0)
	v_mfma_f32_16x16x32_bf16 v[126:129], v[140:143], v[178:181], 0
	v_mfma_f32_16x16x32_bf16 v[118:121], v[154:157], v[178:181], 0
	v_mfma_f32_16x16x32_bf16 v[108:111], v[140:143], v[186:189], 0
	v_mfma_f32_16x16x32_bf16 v[100:103], v[154:157], v[186:189], 0
	v_mfma_f32_16x16x32_bf16 v[92:95], v[140:143], v[230:233], 0
	v_mfma_f32_16x16x32_bf16 v[84:87], v[154:157], v[230:233], 0
	v_mfma_f32_16x16x32_bf16 v[76:79], v[140:143], v[238:241], 0
	v_mfma_f32_16x16x32_bf16 v[68:71], v[154:157], v[238:241], 0
	v_mfma_f32_16x16x32_bf16 v[126:129], v[150:153], v[182:185], v[126:129]
	v_mfma_f32_16x16x32_bf16 v[118:121], v[158:161], v[182:185], v[118:121]
	v_mfma_f32_16x16x32_bf16 v[108:111], v[150:153], v[208:211], v[108:111]
	v_mfma_f32_16x16x32_bf16 v[100:103], v[158:161], v[208:211], v[100:103]
	v_mfma_f32_16x16x32_bf16 v[92:95], v[150:153], v[234:237], v[92:95]
	v_mfma_f32_16x16x32_bf16 v[84:87], v[158:161], v[234:237], v[84:87]
	v_mfma_f32_16x16x32_bf16 v[76:79], v[150:153], v[242:245], v[76:79]
	v_mfma_f32_16x16x32_bf16 v[68:71], v[158:161], v[242:245], v[68:71]
	s_setprio 0
	s_setprio 1
	v_mfma_f32_16x16x32_bf16 v[122:125], v[162:165], v[178:181], 0
	v_mfma_f32_16x16x32_bf16 v[114:117], v[170:173], v[178:181], 0
	v_mfma_f32_16x16x32_bf16 v[104:107], v[162:165], v[186:189], 0
	v_mfma_f32_16x16x32_bf16 v[96:99], v[170:173], v[186:189], 0
	v_mfma_f32_16x16x32_bf16 v[88:91], v[162:165], v[230:233], 0
	v_mfma_f32_16x16x32_bf16 v[80:83], v[170:173], v[230:233], 0
	v_mfma_f32_16x16x32_bf16 v[72:75], v[162:165], v[238:241], 0
	v_mfma_f32_16x16x32_bf16 v[64:67], v[170:173], v[238:241], 0
	v_mfma_f32_16x16x32_bf16 v[122:125], v[166:169], v[182:185], v[122:125]
	v_mfma_f32_16x16x32_bf16 v[114:117], v[174:177], v[182:185], v[114:117]
	v_mfma_f32_16x16x32_bf16 v[104:107], v[166:169], v[208:211], v[104:107]
	v_mfma_f32_16x16x32_bf16 v[96:99], v[174:177], v[208:211], v[96:99]
	v_mfma_f32_16x16x32_bf16 v[88:91], v[166:169], v[234:237], v[88:91]
	v_mfma_f32_16x16x32_bf16 v[80:83], v[174:177], v[234:237], v[80:83]
	v_mfma_f32_16x16x32_bf16 v[72:75], v[166:169], v[242:245], v[72:75]
	v_mfma_f32_16x16x32_bf16 v[64:67], v[174:177], v[242:245], v[64:67]
	s_setprio 0
	s_barrier
	s_add_i32 s55, s55, s35
	s_mov_b32 m0, s55
	ds_read_b128 v[178:181], v149 offset:16384
	ds_read_b128 v[182:185], v149 offset:17408
	ds_read_b128 v[186:189], v149 offset:18432
	ds_read_b128 v[208:211], v149 offset:19456
	ds_read_b128 v[230:233], v149 offset:20480
	ds_read_b128 v[234:237], v149 offset:21504
	ds_read_b128 v[238:241], v149 offset:22528
	ds_read_b128 v[242:245], v149 offset:23552
	global_load_lds_dwordx4 v112, s[26:27]
	s_add_i32 m0, s55, 0x2000
	s_add_u32 s56, s26, 0x40000
	v_lshl_add_u64 v[246:247], s[26:27], 0, v[134:135]
	s_addc_u32 s57, s27, 0
	s_add_i32 s55, s58, s35
	global_load_lds_dwordx4 v134, s[26:27]
	s_mov_b32 m0, s55
	v_lshl_add_u64 v[250:251], s[28:29], 0, v[132:133]
	global_load_lds_dwordx4 v112, s[56:57]
	s_add_i32 m0, s55, 0x2000
	s_nop 0
	global_load_lds_dwordx4 v134, s[56:57]
	v_lshl_add_u64 v[248:249], s[28:29], 0, v[130:131]
	s_mov_b32 m0, s23
	s_nop 0
	global_load_lds_dwordx4 v130, s[28:29]
	s_mov_b32 m0, s44
	s_nop 0
	global_load_lds_dwordx4 v132, s[28:29]
	s_waitcnt vmcnt(8)
	s_waitcnt lgkmcnt(0)
	s_barrier
	s_setprio 1
	s_waitcnt lgkmcnt(0)
	v_mfma_f32_16x16x32_bf16 v[60:63], v[140:143], v[178:181], 0
	v_mfma_f32_16x16x32_bf16 v[52:55], v[154:157], v[178:181], 0
	v_mfma_f32_16x16x32_bf16 v[44:47], v[140:143], v[186:189], 0
	v_mfma_f32_16x16x32_bf16 v[36:39], v[154:157], v[186:189], 0
	v_mfma_f32_16x16x32_bf16 v[28:31], v[140:143], v[230:233], 0
	v_mfma_f32_16x16x32_bf16 v[20:23], v[154:157], v[230:233], 0
	v_mfma_f32_16x16x32_bf16 v[12:15], v[140:143], v[238:241], 0
	v_mfma_f32_16x16x32_bf16 v[4:7], v[154:157], v[238:241], 0
	v_mfma_f32_16x16x32_bf16 v[60:63], v[150:153], v[182:185], v[60:63]
	v_mfma_f32_16x16x32_bf16 v[52:55], v[158:161], v[182:185], v[52:55]
	v_mfma_f32_16x16x32_bf16 v[44:47], v[150:153], v[208:211], v[44:47]
	v_mfma_f32_16x16x32_bf16 v[36:39], v[158:161], v[208:211], v[36:39]
	v_mfma_f32_16x16x32_bf16 v[28:31], v[150:153], v[234:237], v[28:31]
	v_mfma_f32_16x16x32_bf16 v[20:23], v[158:161], v[234:237], v[20:23]
	v_mfma_f32_16x16x32_bf16 v[12:15], v[150:153], v[242:245], v[12:15]
	v_mfma_f32_16x16x32_bf16 v[4:7], v[158:161], v[242:245], v[4:7]
	s_setprio 0
	s_setprio 1
	v_mfma_f32_16x16x32_bf16 v[56:59], v[162:165], v[178:181], 0
	v_mfma_f32_16x16x32_bf16 v[48:51], v[170:173], v[178:181], 0
	v_mfma_f32_16x16x32_bf16 v[40:43], v[162:165], v[186:189], 0
	v_mfma_f32_16x16x32_bf16 v[32:35], v[170:173], v[186:189], 0
	v_mfma_f32_16x16x32_bf16 v[24:27], v[162:165], v[230:233], 0
	v_mfma_f32_16x16x32_bf16 v[16:19], v[170:173], v[230:233], 0
	v_mfma_f32_16x16x32_bf16 v[8:11], v[162:165], v[238:241], 0
	v_mfma_f32_16x16x32_bf16 v[0:3], v[170:173], v[238:241], 0
	v_mfma_f32_16x16x32_bf16 v[56:59], v[166:169], v[182:185], v[56:59]
	v_mfma_f32_16x16x32_bf16 v[48:51], v[174:177], v[182:185], v[48:51]
	v_mfma_f32_16x16x32_bf16 v[40:43], v[166:169], v[208:211], v[40:43]
	v_mfma_f32_16x16x32_bf16 v[32:35], v[174:177], v[208:211], v[32:35]
	v_mfma_f32_16x16x32_bf16 v[24:27], v[166:169], v[234:237], v[24:27]
	v_mfma_f32_16x16x32_bf16 v[16:19], v[174:177], v[234:237], v[16:19]
	v_mfma_f32_16x16x32_bf16 v[8:11], v[166:169], v[242:245], v[8:11]
	v_mfma_f32_16x16x32_bf16 v[0:3], v[174:177], v[242:245], v[0:3]
	s_setprio 0
	s_barrier
	s_add_i32 s55, 0, 0x18000
	v_add_u32_e32 v144, s55, v146
	s_add_i32 s56, 0, 0x1c000
	ds_read_b128 v[140:143], v144
	ds_read_b128 v[150:153], v144 offset:1024
	ds_read_b128 v[154:157], v144 offset:2048
	ds_read_b128 v[158:161], v144 offset:3072
	v_add_u32_e32 v144, s56, v146
	ds_read_b128 v[162:165], v144
	ds_read_b128 v[166:169], v144 offset:1024
	ds_read_b128 v[170:173], v144 offset:2048
	ds_read_b128 v[174:177], v144 offset:3072
	s_add_u32 s28, s28, 0x40000
	s_addc_u32 s29, s29, 0
	s_mov_b32 m0, s45
	ds_read_b128 v[178:181], v149 offset:32768
	ds_read_b128 v[182:185], v149 offset:33792
	ds_read_b128 v[186:189], v149 offset:34816
	ds_read_b128 v[208:211], v149 offset:35840
	ds_read_b128 v[230:233], v149 offset:36864
	ds_read_b128 v[234:237], v149 offset:37888
	ds_read_b128 v[238:241], v149 offset:38912
	ds_read_b128 v[242:245], v149 offset:39936
	global_load_lds_dwordx4 v130, s[28:29]
	s_mov_b32 m0, s46
	s_nop 0
	global_load_lds_dwordx4 v132, s[28:29]
	s_waitcnt vmcnt(8)
	s_waitcnt lgkmcnt(0)
	s_barrier
	s_setprio 1
	s_waitcnt lgkmcnt(0)
	v_mfma_f32_16x16x32_bf16 v[126:129], v[140:143], v[178:181], v[126:129]
	v_mfma_f32_16x16x32_bf16 v[118:121], v[154:157], v[178:181], v[118:121]
	v_mfma_f32_16x16x32_bf16 v[108:111], v[140:143], v[186:189], v[108:111]
	v_mfma_f32_16x16x32_bf16 v[100:103], v[154:157], v[186:189], v[100:103]
	v_mfma_f32_16x16x32_bf16 v[92:95], v[140:143], v[230:233], v[92:95]
	v_mfma_f32_16x16x32_bf16 v[84:87], v[154:157], v[230:233], v[84:87]
	v_mfma_f32_16x16x32_bf16 v[76:79], v[140:143], v[238:241], v[76:79]
	v_mfma_f32_16x16x32_bf16 v[68:71], v[154:157], v[238:241], v[68:71]
	v_mfma_f32_16x16x32_bf16 v[126:129], v[150:153], v[182:185], v[126:129]
	v_mfma_f32_16x16x32_bf16 v[118:121], v[158:161], v[182:185], v[118:121]
	v_mfma_f32_16x16x32_bf16 v[108:111], v[150:153], v[208:211], v[108:111]
	v_mfma_f32_16x16x32_bf16 v[100:103], v[158:161], v[208:211], v[100:103]
	v_mfma_f32_16x16x32_bf16 v[92:95], v[150:153], v[234:237], v[92:95]
	v_mfma_f32_16x16x32_bf16 v[84:87], v[158:161], v[234:237], v[84:87]
	v_mfma_f32_16x16x32_bf16 v[76:79], v[150:153], v[242:245], v[76:79]
	v_mfma_f32_16x16x32_bf16 v[68:71], v[158:161], v[242:245], v[68:71]
	s_setprio 0
	s_setprio 1
	v_mfma_f32_16x16x32_bf16 v[122:125], v[162:165], v[178:181], v[122:125]
	v_mfma_f32_16x16x32_bf16 v[114:117], v[170:173], v[178:181], v[114:117]
	v_mfma_f32_16x16x32_bf16 v[104:107], v[162:165], v[186:189], v[104:107]
	v_mfma_f32_16x16x32_bf16 v[96:99], v[170:173], v[186:189], v[96:99]
	v_mfma_f32_16x16x32_bf16 v[88:91], v[162:165], v[230:233], v[88:91]
	v_mfma_f32_16x16x32_bf16 v[80:83], v[170:173], v[230:233], v[80:83]
	v_mfma_f32_16x16x32_bf16 v[72:75], v[162:165], v[238:241], v[72:75]
	v_mfma_f32_16x16x32_bf16 v[64:67], v[170:173], v[238:241], v[64:67]
	v_mfma_f32_16x16x32_bf16 v[122:125], v[166:169], v[182:185], v[122:125]
	v_mfma_f32_16x16x32_bf16 v[114:117], v[174:177], v[182:185], v[114:117]
	v_mfma_f32_16x16x32_bf16 v[104:107], v[166:169], v[208:211], v[104:107]
	v_mfma_f32_16x16x32_bf16 v[96:99], v[174:177], v[208:211], v[96:99]
	v_mfma_f32_16x16x32_bf16 v[88:91], v[166:169], v[234:237], v[88:91]
	v_mfma_f32_16x16x32_bf16 v[80:83], v[174:177], v[234:237], v[80:83]
	v_mfma_f32_16x16x32_bf16 v[72:75], v[166:169], v[242:245], v[72:75]
	v_mfma_f32_16x16x32_bf16 v[64:67], v[174:177], v[242:245], v[64:67]
	s_setprio 0
	s_barrier
	s_add_i32 s28, s55, s35
	s_mov_b32 m0, s28
	ds_read_b128 v[178:181], v149 offset:49152
	ds_read_b128 v[182:185], v149 offset:50176
	ds_read_b128 v[186:189], v149 offset:51200
	ds_read_b128 v[208:211], v149 offset:52224
	ds_read_b128 v[230:233], v149 offset:53248
	ds_read_b128 v[234:237], v149 offset:54272
	ds_read_b128 v[238:241], v149 offset:55296
	ds_read_b128 v[242:245], v149 offset:56320
	s_add_u32 s98, s26, 0x80
	s_addc_u32 s99, s27, 0
	global_load_lds_dwordx4 v112, s[98:99]
	s_add_i32 m0, s28, 0x2000
	s_add_u32 s26, s26, 0x40080
	v_lshl_add_u64 v[212:213], v[246:247], 0, s[96:97]
	s_addc_u32 s27, s27, 0
	s_add_i32 s28, s56, s35
	global_load_lds_dwordx4 v[212:213], off
	s_mov_b32 m0, s28
	s_nop 0
	global_load_lds_dwordx4 v112, s[26:27]
	s_add_i32 m0, s28, 0x2000
	s_nop 0
	global_load_lds_dwordx4 v134, s[26:27]
	v_lshl_add_u64 v[212:213], v[248:249], 0, s[96:97]
	s_mov_b32 m0, s47
	s_nop 0
	global_load_lds_dwordx4 v[212:213], off
	v_lshl_add_u64 v[212:213], v[250:251], 0, s[96:97]
	s_mov_b32 m0, s48
	s_nop 0
	global_load_lds_dwordx4 v[212:213], off
	s_waitcnt vmcnt(8)
	s_waitcnt lgkmcnt(0)
	s_barrier
	s_setprio 1
	s_waitcnt lgkmcnt(0)
	v_mfma_f32_16x16x32_bf16 v[60:63], v[140:143], v[178:181], v[60:63]
	v_mfma_f32_16x16x32_bf16 v[52:55], v[154:157], v[178:181], v[52:55]
	v_mfma_f32_16x16x32_bf16 v[44:47], v[140:143], v[186:189], v[44:47]
	v_mfma_f32_16x16x32_bf16 v[36:39], v[154:157], v[186:189], v[36:39]
	v_mfma_f32_16x16x32_bf16 v[28:31], v[140:143], v[230:233], v[28:31]
	v_mfma_f32_16x16x32_bf16 v[20:23], v[154:157], v[230:233], v[20:23]
	v_mfma_f32_16x16x32_bf16 v[12:15], v[140:143], v[238:241], v[12:15]
	v_mfma_f32_16x16x32_bf16 v[4:7], v[154:157], v[238:241], v[4:7]
	v_mfma_f32_16x16x32_bf16 v[60:63], v[150:153], v[182:185], v[60:63]
	v_mfma_f32_16x16x32_bf16 v[52:55], v[158:161], v[182:185], v[52:55]
	v_mfma_f32_16x16x32_bf16 v[44:47], v[150:153], v[208:211], v[44:47]
	v_mfma_f32_16x16x32_bf16 v[36:39], v[158:161], v[208:211], v[36:39]
	v_mfma_f32_16x16x32_bf16 v[28:31], v[150:153], v[234:237], v[28:31]
	v_mfma_f32_16x16x32_bf16 v[20:23], v[158:161], v[234:237], v[20:23]
	v_mfma_f32_16x16x32_bf16 v[12:15], v[150:153], v[242:245], v[12:15]
	v_mfma_f32_16x16x32_bf16 v[4:7], v[158:161], v[242:245], v[4:7]
	s_setprio 0
	s_setprio 1
	v_mfma_f32_16x16x32_bf16 v[56:59], v[162:165], v[178:181], v[56:59]
	v_mfma_f32_16x16x32_bf16 v[48:51], v[170:173], v[178:181], v[48:51]
	v_mfma_f32_16x16x32_bf16 v[40:43], v[162:165], v[186:189], v[40:43]
	v_mfma_f32_16x16x32_bf16 v[32:35], v[170:173], v[186:189], v[32:35]
	v_mfma_f32_16x16x32_bf16 v[24:27], v[162:165], v[230:233], v[24:27]
	v_mfma_f32_16x16x32_bf16 v[16:19], v[170:173], v[230:233], v[16:19]
	v_mfma_f32_16x16x32_bf16 v[8:11], v[162:165], v[238:241], v[8:11]
	v_mfma_f32_16x16x32_bf16 v[0:3], v[170:173], v[238:241], v[0:3]
	v_mfma_f32_16x16x32_bf16 v[56:59], v[166:169], v[182:185], v[56:59]
	v_mfma_f32_16x16x32_bf16 v[48:51], v[174:177], v[182:185], v[48:51]
	v_mfma_f32_16x16x32_bf16 v[40:43], v[166:169], v[208:211], v[40:43]
	v_mfma_f32_16x16x32_bf16 v[32:35], v[174:177], v[208:211], v[32:35]
	v_mfma_f32_16x16x32_bf16 v[24:27], v[166:169], v[234:237], v[24:27]
	v_mfma_f32_16x16x32_bf16 v[16:19], v[174:177], v[234:237], v[16:19]
	v_mfma_f32_16x16x32_bf16 v[8:11], v[166:169], v[242:245], v[8:11]
	v_mfma_f32_16x16x32_bf16 v[0:3], v[174:177], v[242:245], v[0:3]
	s_setprio 0
	s_barrier
	s_add_i32 s54, s54, 2
	s_add_u32 s52, s52, 0x100
	s_addc_u32 s53, s53, 0
	s_add_u32 s24, s24, 0x100
	s_addc_u32 s25, s25, 0
	s_cmp_gt_u32 s54, 13
	s_cbranch_scc0 .LBB0_1952
	s_branch .Lpeel_exit_1952
	.p2align 6

.LBB0_2150:
	s_ashr_i32 s29, s28, 31
	s_lshl_b64 s[30:31], s[28:29], 19
	s_add_u32 s30, s49, s30
	s_addc_u32 s31, s50, s31
	s_and_b64 s[40:41], s[6:7], exec
	s_cselect_b32 s11, s31, s39
	s_cselect_b32 s29, s30, s38
	s_ashr_i32 s27, s26, 31
	s_lshl_b64 s[40:41], s[26:27], 19
	s_add_u32 s46, s51, s40
	s_addc_u32 s47, s52, s41
	s_and_b64 s[40:41], s[6:7], exec
	s_cselect_b32 s27, s47, s9
	s_cselect_b32 s35, s46, s8
	s_add_u32 s42, s8, 0x100
	s_addc_u32 s43, s9, 0
	s_add_u32 s8, s38, 0x40080
	s_addc_u32 s9, s39, 0
	s_mov_b32 s44, -2
	s_add_u32 s38, s8, 0xfffc0080
	s_addc_u32 s39, s9, -1
	s_add_i32 s45, 0, 0x10000
	s_cmp_eq_u32 s44, 12
	s_cselect_b32 s41, s11, s39
	s_cselect_b32 s40, s29, s38
	v_add_u32_e32 v112, s45, v169
	s_cselect_b32 s39, s27, s43
	s_cselect_b32 s38, s35, s42
	s_add_i32 s68, 0, 0x14000
	ds_read_b128 v[130:133], v112
	ds_read_b128 v[134:137], v112 offset:1024
	ds_read_b128 v[150:153], v112 offset:2048
	ds_read_b128 v[154:157], v112 offset:3072
	v_add_u32_e32 v112, s68, v169
	ds_read_b128 v[158:161], v112
	ds_read_b128 v[162:165], v112 offset:1024
	ds_read_b128 v[174:177], v112 offset:2048
	ds_read_b128 v[178:181], v112 offset:3072
	s_add_i32 m0, s37, 0xc000
	ds_read_b128 v[182:185], v172
	ds_read_b128 v[186:189], v172 offset:1024
	ds_read_b128 v[208:211], v172 offset:2048
	ds_read_b128 v[230:233], v172 offset:3072
	ds_read_b128 v[234:237], v172 offset:4096
	ds_read_b128 v[238:241], v172 offset:5120
	ds_read_b128 v[242:245], v172 offset:6144
	ds_read_b128 v[246:249], v172 offset:7168
	global_load_lds_dwordx4 v148, s[8:9]
	s_add_i32 m0, s37, 0xe000
	s_nop 0
	global_load_lds_dwordx4 v146, s[8:9]
	s_waitcnt vmcnt(8)
	s_waitcnt lgkmcnt(0)
	s_barrier
	s_setprio 1
	s_waitcnt lgkmcnt(0)
	v_mfma_f32_16x16x32_bf16 v[126:129], v[130:133], v[182:185], 0
	v_mfma_f32_16x16x32_bf16 v[122:125], v[150:153], v[182:185], 0
	v_mfma_f32_16x16x32_bf16 v[108:111], v[130:133], v[208:211], 0
	v_mfma_f32_16x16x32_bf16 v[104:107], v[150:153], v[208:211], 0
	v_mfma_f32_16x16x32_bf16 v[92:95], v[130:133], v[234:237], 0
	v_mfma_f32_16x16x32_bf16 v[88:91], v[150:153], v[234:237], 0
	v_mfma_f32_16x16x32_bf16 v[76:79], v[130:133], v[242:245], 0
	v_mfma_f32_16x16x32_bf16 v[72:75], v[150:153], v[242:245], 0
	v_mfma_f32_16x16x32_bf16 v[126:129], v[134:137], v[186:189], v[126:129]
	v_mfma_f32_16x16x32_bf16 v[122:125], v[154:157], v[186:189], v[122:125]
	v_mfma_f32_16x16x32_bf16 v[108:111], v[134:137], v[230:233], v[108:111]
	v_mfma_f32_16x16x32_bf16 v[104:107], v[154:157], v[230:233], v[104:107]
	v_mfma_f32_16x16x32_bf16 v[92:95], v[134:137], v[238:241], v[92:95]
	v_mfma_f32_16x16x32_bf16 v[88:91], v[154:157], v[238:241], v[88:91]
	v_mfma_f32_16x16x32_bf16 v[76:79], v[134:137], v[246:249], v[76:79]
	v_mfma_f32_16x16x32_bf16 v[72:75], v[154:157], v[246:249], v[72:75]
	s_setprio 0
	s_setprio 1
	v_mfma_f32_16x16x32_bf16 v[118:121], v[158:161], v[182:185], 0
	v_mfma_f32_16x16x32_bf16 v[114:117], v[174:177], v[182:185], 0
	v_mfma_f32_16x16x32_bf16 v[100:103], v[158:161], v[208:211], 0
	v_mfma_f32_16x16x32_bf16 v[96:99], v[174:177], v[208:211], 0
	v_mfma_f32_16x16x32_bf16 v[84:87], v[158:161], v[234:237], 0
	v_mfma_f32_16x16x32_bf16 v[80:83], v[174:177], v[234:237], 0
	v_mfma_f32_16x16x32_bf16 v[68:71], v[158:161], v[242:245], 0
	v_mfma_f32_16x16x32_bf16 v[64:67], v[174:177], v[242:245], 0
	v_mfma_f32_16x16x32_bf16 v[118:121], v[162:165], v[186:189], v[118:121]
	v_mfma_f32_16x16x32_bf16 v[114:117], v[178:181], v[186:189], v[114:117]
	v_mfma_f32_16x16x32_bf16 v[100:103], v[162:165], v[230:233], v[100:103]
	v_mfma_f32_16x16x32_bf16 v[96:99], v[178:181], v[230:233], v[96:99]
	v_mfma_f32_16x16x32_bf16 v[84:87], v[162:165], v[238:241], v[84:87]
	v_mfma_f32_16x16x32_bf16 v[80:83], v[178:181], v[238:241], v[80:83]
	v_mfma_f32_16x16x32_bf16 v[68:71], v[162:165], v[246:249], v[68:71]
	v_mfma_f32_16x16x32_bf16 v[64:67], v[178:181], v[246:249], v[64:67]
	s_setprio 0
	s_barrier
	s_add_i32 s45, s45, s58
	s_mov_b32 m0, s45
	ds_read_b128 v[182:185], v172 offset:16384
	ds_read_b128 v[186:189], v172 offset:17408
	ds_read_b128 v[208:211], v172 offset:18432
	ds_read_b128 v[230:233], v172 offset:19456
	ds_read_b128 v[234:237], v172 offset:20480
	ds_read_b128 v[238:241], v172 offset:21504
	ds_read_b128 v[242:245], v172 offset:22528
	ds_read_b128 v[246:249], v172 offset:23552
	global_load_lds_dwordx4 v140, s[38:39]
	s_add_i32 m0, s45, 0x2000
	s_add_u32 s66, s38, 0x40000
	v_lshl_add_u64 v[212:213], s[38:39], 0, v[144:145]
	s_addc_u32 s67, s39, 0
	s_add_i32 s45, s68, s58
	global_load_lds_dwordx4 v144, s[38:39]
	s_mov_b32 m0, s45
	v_lshl_add_u64 v[250:251], s[40:41], 0, v[142:143]
	global_load_lds_dwordx4 v140, s[66:67]
	s_add_i32 m0, s45, 0x2000
	s_nop 0
	global_load_lds_dwordx4 v144, s[66:67]
	v_lshl_add_u64 v[228:229], s[40:41], 0, v[138:139]
	s_mov_b32 m0, s37
	s_nop 0
	global_load_lds_dwordx4 v138, s[40:41]
	s_mov_b32 m0, s59
	s_nop 0
	global_load_lds_dwordx4 v142, s[40:41]
	s_waitcnt vmcnt(8)
	s_waitcnt lgkmcnt(0)
	s_barrier
	s_setprio 1
	s_waitcnt lgkmcnt(0)
	v_mfma_f32_16x16x32_bf16 v[60:63], v[130:133], v[182:185], 0
	v_mfma_f32_16x16x32_bf16 v[56:59], v[150:153], v[182:185], 0
	v_mfma_f32_16x16x32_bf16 v[44:47], v[130:133], v[208:211], 0
	v_mfma_f32_16x16x32_bf16 v[40:43], v[150:153], v[208:211], 0
	v_mfma_f32_16x16x32_bf16 v[28:31], v[130:133], v[234:237], 0
	v_mfma_f32_16x16x32_bf16 v[24:27], v[150:153], v[234:237], 0
	v_mfma_f32_16x16x32_bf16 v[12:15], v[130:133], v[242:245], 0
	v_mfma_f32_16x16x32_bf16 v[8:11], v[150:153], v[242:245], 0
	v_mfma_f32_16x16x32_bf16 v[60:63], v[134:137], v[186:189], v[60:63]
	v_mfma_f32_16x16x32_bf16 v[56:59], v[154:157], v[186:189], v[56:59]
	v_mfma_f32_16x16x32_bf16 v[44:47], v[134:137], v[230:233], v[44:47]
	v_mfma_f32_16x16x32_bf16 v[40:43], v[154:157], v[230:233], v[40:43]
	v_mfma_f32_16x16x32_bf16 v[28:31], v[134:137], v[238:241], v[28:31]
	v_mfma_f32_16x16x32_bf16 v[24:27], v[154:157], v[238:241], v[24:27]
	v_mfma_f32_16x16x32_bf16 v[12:15], v[134:137], v[246:249], v[12:15]
	v_mfma_f32_16x16x32_bf16 v[8:11], v[154:157], v[246:249], v[8:11]
	s_setprio 0
	s_setprio 1
	v_mfma_f32_16x16x32_bf16 v[52:55], v[158:161], v[182:185], 0
	v_mfma_f32_16x16x32_bf16 v[48:51], v[174:177], v[182:185], 0
	v_mfma_f32_16x16x32_bf16 v[36:39], v[158:161], v[208:211], 0
	v_mfma_f32_16x16x32_bf16 v[32:35], v[174:177], v[208:211], 0
	v_mfma_f32_16x16x32_bf16 v[20:23], v[158:161], v[234:237], 0
	v_mfma_f32_16x16x32_bf16 v[16:19], v[174:177], v[234:237], 0
	v_mfma_f32_16x16x32_bf16 v[4:7], v[158:161], v[242:245], 0
	v_mfma_f32_16x16x32_bf16 v[0:3], v[174:177], v[242:245], 0
	v_mfma_f32_16x16x32_bf16 v[52:55], v[162:165], v[186:189], v[52:55]
	v_mfma_f32_16x16x32_bf16 v[48:51], v[178:181], v[186:189], v[48:51]
	v_mfma_f32_16x16x32_bf16 v[36:39], v[162:165], v[230:233], v[36:39]
	v_mfma_f32_16x16x32_bf16 v[32:35], v[178:181], v[230:233], v[32:35]
	v_mfma_f32_16x16x32_bf16 v[20:23], v[162:165], v[238:241], v[20:23]
	v_mfma_f32_16x16x32_bf16 v[16:19], v[178:181], v[238:241], v[16:19]
	v_mfma_f32_16x16x32_bf16 v[4:7], v[162:165], v[246:249], v[4:7]
	v_mfma_f32_16x16x32_bf16 v[0:3], v[178:181], v[246:249], v[0:3]
	s_setprio 0
	s_barrier
	s_add_i32 s45, 0, 0x18000
	v_add_u32_e32 v112, s45, v169
	s_add_i32 s66, 0, 0x1c000
	ds_read_b128 v[130:133], v112
	ds_read_b128 v[134:137], v112 offset:1024
	ds_read_b128 v[150:153], v112 offset:2048
	ds_read_b128 v[154:157], v112 offset:3072
	v_add_u32_e32 v112, s66, v169
	ds_read_b128 v[158:161], v112
	ds_read_b128 v[162:165], v112 offset:1024
	ds_read_b128 v[174:177], v112 offset:2048
	ds_read_b128 v[178:181], v112 offset:3072
	s_add_u32 s40, s40, 0x40000
	s_addc_u32 s41, s41, 0
	s_mov_b32 m0, s60
	ds_read_b128 v[182:185], v172 offset:32768
	ds_read_b128 v[186:189], v172 offset:33792
	ds_read_b128 v[208:211], v172 offset:34816
	ds_read_b128 v[230:233], v172 offset:35840
	ds_read_b128 v[234:237], v172 offset:36864
	ds_read_b128 v[238:241], v172 offset:37888
	ds_read_b128 v[242:245], v172 offset:38912
	ds_read_b128 v[246:249], v172 offset:39936
	global_load_lds_dwordx4 v138, s[40:41]
	s_mov_b32 m0, s61
	s_nop 0
	global_load_lds_dwordx4 v142, s[40:41]
	s_waitcnt vmcnt(8)
	s_waitcnt lgkmcnt(0)
	s_barrier
	s_setprio 1
	s_waitcnt lgkmcnt(0)
	v_mfma_f32_16x16x32_bf16 v[126:129], v[130:133], v[182:185], v[126:129]
	v_mfma_f32_16x16x32_bf16 v[122:125], v[150:153], v[182:185], v[122:125]
	v_mfma_f32_16x16x32_bf16 v[108:111], v[130:133], v[208:211], v[108:111]
	v_mfma_f32_16x16x32_bf16 v[104:107], v[150:153], v[208:211], v[104:107]
	v_mfma_f32_16x16x32_bf16 v[92:95], v[130:133], v[234:237], v[92:95]
	v_mfma_f32_16x16x32_bf16 v[88:91], v[150:153], v[234:237], v[88:91]
	v_mfma_f32_16x16x32_bf16 v[76:79], v[130:133], v[242:245], v[76:79]
	v_mfma_f32_16x16x32_bf16 v[72:75], v[150:153], v[242:245], v[72:75]
	v_mfma_f32_16x16x32_bf16 v[126:129], v[134:137], v[186:189], v[126:129]
	v_mfma_f32_16x16x32_bf16 v[122:125], v[154:157], v[186:189], v[122:125]
	v_mfma_f32_16x16x32_bf16 v[108:111], v[134:137], v[230:233], v[108:111]
	v_mfma_f32_16x16x32_bf16 v[104:107], v[154:157], v[230:233], v[104:107]
	v_mfma_f32_16x16x32_bf16 v[92:95], v[134:137], v[238:241], v[92:95]
	v_mfma_f32_16x16x32_bf16 v[88:91], v[154:157], v[238:241], v[88:91]
	v_mfma_f32_16x16x32_bf16 v[76:79], v[134:137], v[246:249], v[76:79]
	v_mfma_f32_16x16x32_bf16 v[72:75], v[154:157], v[246:249], v[72:75]
	s_setprio 0
	s_setprio 1
	v_mfma_f32_16x16x32_bf16 v[118:121], v[158:161], v[182:185], v[118:121]
	v_mfma_f32_16x16x32_bf16 v[114:117], v[174:177], v[182:185], v[114:117]
	v_mfma_f32_16x16x32_bf16 v[100:103], v[158:161], v[208:211], v[100:103]
	v_mfma_f32_16x16x32_bf16 v[96:99], v[174:177], v[208:211], v[96:99]
	v_mfma_f32_16x16x32_bf16 v[84:87], v[158:161], v[234:237], v[84:87]
	v_mfma_f32_16x16x32_bf16 v[80:83], v[174:177], v[234:237], v[80:83]
	v_mfma_f32_16x16x32_bf16 v[68:71], v[158:161], v[242:245], v[68:71]
	v_mfma_f32_16x16x32_bf16 v[64:67], v[174:177], v[242:245], v[64:67]
	v_mfma_f32_16x16x32_bf16 v[118:121], v[162:165], v[186:189], v[118:121]
	v_mfma_f32_16x16x32_bf16 v[114:117], v[178:181], v[186:189], v[114:117]
	v_mfma_f32_16x16x32_bf16 v[100:103], v[162:165], v[230:233], v[100:103]
	v_mfma_f32_16x16x32_bf16 v[96:99], v[178:181], v[230:233], v[96:99]
	v_mfma_f32_16x16x32_bf16 v[84:87], v[162:165], v[238:241], v[84:87]
	v_mfma_f32_16x16x32_bf16 v[80:83], v[178:181], v[238:241], v[80:83]
	v_mfma_f32_16x16x32_bf16 v[68:71], v[162:165], v[246:249], v[68:71]
	v_mfma_f32_16x16x32_bf16 v[64:67], v[178:181], v[246:249], v[64:67]
	s_setprio 0
	s_barrier
	s_add_i32 s40, s45, s58
	s_mov_b32 m0, s40
	ds_read_b128 v[182:185], v172 offset:49152
	ds_read_b128 v[186:189], v172 offset:50176
	ds_read_b128 v[208:211], v172 offset:51200
	ds_read_b128 v[230:233], v172 offset:52224
	ds_read_b128 v[234:237], v172 offset:53248
	ds_read_b128 v[238:241], v172 offset:54272
	ds_read_b128 v[242:245], v172 offset:55296
	ds_read_b128 v[246:249], v172 offset:56320
	s_add_u32 s98, s38, 0x80
	s_addc_u32 s99, s39, 0
	global_load_lds_dwordx4 v140, s[98:99]
	s_add_i32 m0, s40, 0x2000
	s_add_u32 s38, s38, 0x40080
	v_lshl_add_u64 v[166:167], v[212:213], 0, s[96:97]
	s_addc_u32 s39, s39, 0
	s_add_i32 s40, s66, s58
	global_load_lds_dwordx4 v[166:167], off
	s_mov_b32 m0, s40
	s_nop 0
	global_load_lds_dwordx4 v140, s[38:39]
	s_add_i32 m0, s40, 0x2000
	s_nop 0
	global_load_lds_dwordx4 v144, s[38:39]
	v_lshl_add_u64 v[166:167], v[228:229], 0, s[96:97]
	s_mov_b32 m0, s62
	s_nop 0
	global_load_lds_dwordx4 v[166:167], off
	v_lshl_add_u64 v[166:167], v[250:251], 0, s[96:97]
	s_mov_b32 m0, s63
	s_nop 0
	global_load_lds_dwordx4 v[166:167], off
	s_waitcnt vmcnt(8)
	s_waitcnt lgkmcnt(0)
	s_barrier
	s_setprio 1
	s_waitcnt lgkmcnt(0)
	v_mfma_f32_16x16x32_bf16 v[60:63], v[130:133], v[182:185], v[60:63]
	v_mfma_f32_16x16x32_bf16 v[56:59], v[150:153], v[182:185], v[56:59]
	v_mfma_f32_16x16x32_bf16 v[44:47], v[130:133], v[208:211], v[44:47]
	v_mfma_f32_16x16x32_bf16 v[40:43], v[150:153], v[208:211], v[40:43]
	v_mfma_f32_16x16x32_bf16 v[28:31], v[130:133], v[234:237], v[28:31]
	v_mfma_f32_16x16x32_bf16 v[24:27], v[150:153], v[234:237], v[24:27]
	v_mfma_f32_16x16x32_bf16 v[12:15], v[130:133], v[242:245], v[12:15]
	v_mfma_f32_16x16x32_bf16 v[8:11], v[150:153], v[242:245], v[8:11]
	v_mfma_f32_16x16x32_bf16 v[60:63], v[134:137], v[186:189], v[60:63]
	v_mfma_f32_16x16x32_bf16 v[56:59], v[154:157], v[186:189], v[56:59]
	v_mfma_f32_16x16x32_bf16 v[44:47], v[134:137], v[230:233], v[44:47]
	v_mfma_f32_16x16x32_bf16 v[40:43], v[154:157], v[230:233], v[40:43]
	v_mfma_f32_16x16x32_bf16 v[28:31], v[134:137], v[238:241], v[28:31]
	v_mfma_f32_16x16x32_bf16 v[24:27], v[154:157], v[238:241], v[24:27]
	v_mfma_f32_16x16x32_bf16 v[12:15], v[134:137], v[246:249], v[12:15]
	v_mfma_f32_16x16x32_bf16 v[8:11], v[154:157], v[246:249], v[8:11]
	s_setprio 0
	s_setprio 1
	v_mfma_f32_16x16x32_bf16 v[52:55], v[158:161], v[182:185], v[52:55]
	v_mfma_f32_16x16x32_bf16 v[48:51], v[174:177], v[182:185], v[48:51]
	v_mfma_f32_16x16x32_bf16 v[36:39], v[158:161], v[208:211], v[36:39]
	v_mfma_f32_16x16x32_bf16 v[32:35], v[174:177], v[208:211], v[32:35]
	v_mfma_f32_16x16x32_bf16 v[20:23], v[158:161], v[234:237], v[20:23]
	v_mfma_f32_16x16x32_bf16 v[16:19], v[174:177], v[234:237], v[16:19]
	v_mfma_f32_16x16x32_bf16 v[4:7], v[158:161], v[242:245], v[4:7]
	v_mfma_f32_16x16x32_bf16 v[0:3], v[174:177], v[242:245], v[0:3]
	v_mfma_f32_16x16x32_bf16 v[52:55], v[162:165], v[186:189], v[52:55]
	v_mfma_f32_16x16x32_bf16 v[48:51], v[178:181], v[186:189], v[48:51]
	v_mfma_f32_16x16x32_bf16 v[36:39], v[162:165], v[230:233], v[36:39]
	v_mfma_f32_16x16x32_bf16 v[32:35], v[178:181], v[230:233], v[32:35]
	v_mfma_f32_16x16x32_bf16 v[20:23], v[162:165], v[238:241], v[20:23]
	v_mfma_f32_16x16x32_bf16 v[16:19], v[178:181], v[238:241], v[16:19]
	v_mfma_f32_16x16x32_bf16 v[4:7], v[162:165], v[246:249], v[4:7]
	v_mfma_f32_16x16x32_bf16 v[0:3], v[178:181], v[246:249], v[0:3]
	s_setprio 0
	s_barrier
	s_add_i32 s44, s44, 2
	s_add_u32 s42, s42, 0x100
	s_addc_u32 s43, s43, 0
	s_add_u32 s8, s8, 0x100
	s_addc_u32 s9, s9, 0
	s_cmp_gt_u32 s44, 13
	s_cbranch_scc0 .LBB0_2151
	s_branch .Lpeel_exit_2151
	.p2align 6

.LBB0_2368:
	s_ashr_i32 s23, s22, 31
	s_lshl_b64 s[24:25], s[22:23], 19
	s_add_u32 s24, s49, s24
	s_addc_u32 s25, s50, s25
	s_and_b64 s[26:27], s[2:3], exec
	s_cselect_b32 s5, s25, s29
	s_cselect_b32 s23, s24, s28
	s_ashr_i32 s15, s14, 31
	s_lshl_b64 s[26:27], s[14:15], 19
	s_add_u32 s26, s51, s26
	s_addc_u32 s27, s52, s27
	s_and_b64 s[30:31], s[2:3], exec
	s_cselect_b32 s15, s27, s7
	s_cselect_b32 s47, s26, s6
	s_add_u32 s54, s6, 0x100
	s_addc_u32 s55, s7, 0
	s_add_u32 s6, s28, 0x40080
	s_addc_u32 s7, s29, 0
	s_mov_b32 s56, -2
	s_waitcnt lgkmcnt(0)
	s_add_u32 s28, s6, 0xfffc0080
	s_addc_u32 s29, s7, -1
	s_add_i32 s57, 0, 0x10000
	s_cmp_eq_u32 s56, 12
	s_cselect_b32 s31, s5, s29
	s_cselect_b32 s30, s23, s28
	v_add_u32_e32 v146, s57, v148
	s_cselect_b32 s29, s15, s55
	s_cselect_b32 s28, s47, s54
	s_add_i32 s60, 0, 0x14000
	ds_read_b128 v[142:145], v146
	ds_read_b128 v[152:155], v146 offset:1024
	ds_read_b128 v[156:159], v146 offset:2048
	ds_read_b128 v[160:163], v146 offset:3072
	v_add_u32_e32 v146, s60, v148
	ds_read_b128 v[164:167], v146
	ds_read_b128 v[168:171], v146 offset:1024
	ds_read_b128 v[172:175], v146 offset:2048
	ds_read_b128 v[176:179], v146 offset:3072
	s_add_i32 m0, s21, 0xc000
	ds_read_b128 v[180:183], v151
	ds_read_b128 v[184:187], v151 offset:1024
	ds_read_b128 v[208:211], v151 offset:2048
	ds_read_b128 v[230:233], v151 offset:3072
	ds_read_b128 v[234:237], v151 offset:4096
	ds_read_b128 v[238:241], v151 offset:5120
	ds_read_b128 v[242:245], v151 offset:6144
	ds_read_b128 v[246:249], v151 offset:7168
	global_load_lds_dwordx4 v140, s[6:7]
	s_add_i32 m0, s21, 0xe000
	s_nop 0
	global_load_lds_dwordx4 v138, s[6:7]
	s_waitcnt vmcnt(8)
	s_waitcnt lgkmcnt(0)
	s_barrier
	s_setprio 1
	s_waitcnt lgkmcnt(0)
	v_mfma_f32_16x16x32_bf16 v[126:129], v[142:145], v[180:183], 0
	v_mfma_f32_16x16x32_bf16 v[122:125], v[156:159], v[180:183], 0
	v_mfma_f32_16x16x32_bf16 v[108:111], v[142:145], v[208:211], 0
	v_mfma_f32_16x16x32_bf16 v[104:107], v[156:159], v[208:211], 0
	v_mfma_f32_16x16x32_bf16 v[92:95], v[142:145], v[234:237], 0
	v_mfma_f32_16x16x32_bf16 v[88:91], v[156:159], v[234:237], 0
	v_mfma_f32_16x16x32_bf16 v[76:79], v[142:145], v[242:245], 0
	v_mfma_f32_16x16x32_bf16 v[72:75], v[156:159], v[242:245], 0
	v_mfma_f32_16x16x32_bf16 v[126:129], v[152:155], v[184:187], v[126:129]
	v_mfma_f32_16x16x32_bf16 v[122:125], v[160:163], v[184:187], v[122:125]
	v_mfma_f32_16x16x32_bf16 v[108:111], v[152:155], v[230:233], v[108:111]
	v_mfma_f32_16x16x32_bf16 v[104:107], v[160:163], v[230:233], v[104:107]
	v_mfma_f32_16x16x32_bf16 v[92:95], v[152:155], v[238:241], v[92:95]
	v_mfma_f32_16x16x32_bf16 v[88:91], v[160:163], v[238:241], v[88:91]
	v_mfma_f32_16x16x32_bf16 v[76:79], v[152:155], v[246:249], v[76:79]
	v_mfma_f32_16x16x32_bf16 v[72:75], v[160:163], v[246:249], v[72:75]
	s_setprio 0
	s_setprio 1
	v_mfma_f32_16x16x32_bf16 v[118:121], v[164:167], v[180:183], 0
	v_mfma_f32_16x16x32_bf16 v[114:117], v[172:175], v[180:183], 0
	v_mfma_f32_16x16x32_bf16 v[100:103], v[164:167], v[208:211], 0
	v_mfma_f32_16x16x32_bf16 v[96:99], v[172:175], v[208:211], 0
	v_mfma_f32_16x16x32_bf16 v[84:87], v[164:167], v[234:237], 0
	v_mfma_f32_16x16x32_bf16 v[80:83], v[172:175], v[234:237], 0
	v_mfma_f32_16x16x32_bf16 v[68:71], v[164:167], v[242:245], 0
	v_mfma_f32_16x16x32_bf16 v[64:67], v[172:175], v[242:245], 0
	v_mfma_f32_16x16x32_bf16 v[118:121], v[168:171], v[184:187], v[118:121]
	v_mfma_f32_16x16x32_bf16 v[114:117], v[176:179], v[184:187], v[114:117]
	v_mfma_f32_16x16x32_bf16 v[100:103], v[168:171], v[230:233], v[100:103]
	v_mfma_f32_16x16x32_bf16 v[96:99], v[176:179], v[230:233], v[96:99]
	v_mfma_f32_16x16x32_bf16 v[84:87], v[168:171], v[238:241], v[84:87]
	v_mfma_f32_16x16x32_bf16 v[80:83], v[176:179], v[238:241], v[80:83]
	v_mfma_f32_16x16x32_bf16 v[68:71], v[168:171], v[246:249], v[68:71]
	v_mfma_f32_16x16x32_bf16 v[64:67], v[176:179], v[246:249], v[64:67]
	s_setprio 0
	s_barrier
	s_add_i32 s57, s57, s39
	s_mov_b32 m0, s57
	ds_read_b128 v[180:183], v151 offset:16384
	ds_read_b128 v[184:187], v151 offset:17408
	ds_read_b128 v[208:211], v151 offset:18432
	ds_read_b128 v[230:233], v151 offset:19456
	ds_read_b128 v[234:237], v151 offset:20480
	ds_read_b128 v[238:241], v151 offset:21504
	ds_read_b128 v[242:245], v151 offset:22528
	ds_read_b128 v[246:249], v151 offset:23552
	global_load_lds_dwordx4 v112, s[28:29]
	s_add_i32 m0, s57, 0x2000
	s_add_u32 s58, s28, 0x40000
	v_lshl_add_u64 v[212:213], s[28:29], 0, v[134:135]
	s_addc_u32 s59, s29, 0
	s_add_i32 s57, s60, s39
	global_load_lds_dwordx4 v134, s[28:29]
	s_mov_b32 m0, s57
	v_lshl_add_u64 v[252:253], s[30:31], 0, v[132:133]
	global_load_lds_dwordx4 v112, s[58:59]
	s_add_i32 m0, s57, 0x2000
	s_nop 0
	global_load_lds_dwordx4 v134, s[58:59]
	v_lshl_add_u64 v[250:251], s[30:31], 0, v[130:131]
	s_mov_b32 m0, s21
	s_nop 0
	global_load_lds_dwordx4 v130, s[30:31]
	s_mov_b32 m0, s40
	s_nop 0
	global_load_lds_dwordx4 v132, s[30:31]
	s_waitcnt vmcnt(8)
	s_waitcnt lgkmcnt(0)
	s_barrier
	s_setprio 1
	s_waitcnt lgkmcnt(0)
	v_mfma_f32_16x16x32_bf16 v[60:63], v[142:145], v[180:183], 0
	v_mfma_f32_16x16x32_bf16 v[56:59], v[156:159], v[180:183], 0
	v_mfma_f32_16x16x32_bf16 v[44:47], v[142:145], v[208:211], 0
	v_mfma_f32_16x16x32_bf16 v[40:43], v[156:159], v[208:211], 0
	v_mfma_f32_16x16x32_bf16 v[28:31], v[142:145], v[234:237], 0
	v_mfma_f32_16x16x32_bf16 v[24:27], v[156:159], v[234:237], 0
	v_mfma_f32_16x16x32_bf16 v[12:15], v[142:145], v[242:245], 0
	v_mfma_f32_16x16x32_bf16 v[8:11], v[156:159], v[242:245], 0
	v_mfma_f32_16x16x32_bf16 v[60:63], v[152:155], v[184:187], v[60:63]
	v_mfma_f32_16x16x32_bf16 v[56:59], v[160:163], v[184:187], v[56:59]
	v_mfma_f32_16x16x32_bf16 v[44:47], v[152:155], v[230:233], v[44:47]
	v_mfma_f32_16x16x32_bf16 v[40:43], v[160:163], v[230:233], v[40:43]
	v_mfma_f32_16x16x32_bf16 v[28:31], v[152:155], v[238:241], v[28:31]
	v_mfma_f32_16x16x32_bf16 v[24:27], v[160:163], v[238:241], v[24:27]
	v_mfma_f32_16x16x32_bf16 v[12:15], v[152:155], v[246:249], v[12:15]
	v_mfma_f32_16x16x32_bf16 v[8:11], v[160:163], v[246:249], v[8:11]
	s_setprio 0
	s_setprio 1
	v_mfma_f32_16x16x32_bf16 v[52:55], v[164:167], v[180:183], 0
	v_mfma_f32_16x16x32_bf16 v[48:51], v[172:175], v[180:183], 0
	v_mfma_f32_16x16x32_bf16 v[36:39], v[164:167], v[208:211], 0
	v_mfma_f32_16x16x32_bf16 v[32:35], v[172:175], v[208:211], 0
	v_mfma_f32_16x16x32_bf16 v[20:23], v[164:167], v[234:237], 0
	v_mfma_f32_16x16x32_bf16 v[16:19], v[172:175], v[234:237], 0
	v_mfma_f32_16x16x32_bf16 v[4:7], v[164:167], v[242:245], 0
	v_mfma_f32_16x16x32_bf16 v[0:3], v[172:175], v[242:245], 0
	v_mfma_f32_16x16x32_bf16 v[52:55], v[168:171], v[184:187], v[52:55]
	v_mfma_f32_16x16x32_bf16 v[48:51], v[176:179], v[184:187], v[48:51]
	v_mfma_f32_16x16x32_bf16 v[36:39], v[168:171], v[230:233], v[36:39]
	v_mfma_f32_16x16x32_bf16 v[32:35], v[176:179], v[230:233], v[32:35]
	v_mfma_f32_16x16x32_bf16 v[20:23], v[168:171], v[238:241], v[20:23]
	v_mfma_f32_16x16x32_bf16 v[16:19], v[176:179], v[238:241], v[16:19]
	v_mfma_f32_16x16x32_bf16 v[4:7], v[168:171], v[246:249], v[4:7]
	v_mfma_f32_16x16x32_bf16 v[0:3], v[176:179], v[246:249], v[0:3]
	s_setprio 0
	s_barrier
	s_add_i32 s57, 0, 0x18000
	v_add_u32_e32 v146, s57, v148
	s_add_i32 s58, 0, 0x1c000
	ds_read_b128 v[142:145], v146
	ds_read_b128 v[152:155], v146 offset:1024
	ds_read_b128 v[156:159], v146 offset:2048
	ds_read_b128 v[160:163], v146 offset:3072
	v_add_u32_e32 v146, s58, v148
	ds_read_b128 v[164:167], v146
	ds_read_b128 v[168:171], v146 offset:1024
	ds_read_b128 v[172:175], v146 offset:2048
	ds_read_b128 v[176:179], v146 offset:3072
	s_add_u32 s30, s30, 0x40000
	s_addc_u32 s31, s31, 0
	s_mov_b32 m0, s41
	ds_read_b128 v[180:183], v151 offset:32768
	ds_read_b128 v[184:187], v151 offset:33792
	ds_read_b128 v[208:211], v151 offset:34816
	ds_read_b128 v[230:233], v151 offset:35840
	ds_read_b128 v[234:237], v151 offset:36864
	ds_read_b128 v[238:241], v151 offset:37888
	ds_read_b128 v[242:245], v151 offset:38912
	ds_read_b128 v[246:249], v151 offset:39936
	global_load_lds_dwordx4 v130, s[30:31]
	s_mov_b32 m0, s42
	s_nop 0
	global_load_lds_dwordx4 v132, s[30:31]
	s_waitcnt vmcnt(8)
	s_waitcnt lgkmcnt(0)
	s_barrier
	s_setprio 1
	s_waitcnt lgkmcnt(0)
	v_mfma_f32_16x16x32_bf16 v[126:129], v[142:145], v[180:183], v[126:129]
	v_mfma_f32_16x16x32_bf16 v[122:125], v[156:159], v[180:183], v[122:125]
	v_mfma_f32_16x16x32_bf16 v[108:111], v[142:145], v[208:211], v[108:111]
	v_mfma_f32_16x16x32_bf16 v[104:107], v[156:159], v[208:211], v[104:107]
	v_mfma_f32_16x16x32_bf16 v[92:95], v[142:145], v[234:237], v[92:95]
	v_mfma_f32_16x16x32_bf16 v[88:91], v[156:159], v[234:237], v[88:91]
	v_mfma_f32_16x16x32_bf16 v[76:79], v[142:145], v[242:245], v[76:79]
	v_mfma_f32_16x16x32_bf16 v[72:75], v[156:159], v[242:245], v[72:75]
	v_mfma_f32_16x16x32_bf16 v[126:129], v[152:155], v[184:187], v[126:129]
	v_mfma_f32_16x16x32_bf16 v[122:125], v[160:163], v[184:187], v[122:125]
	v_mfma_f32_16x16x32_bf16 v[108:111], v[152:155], v[230:233], v[108:111]
	v_mfma_f32_16x16x32_bf16 v[104:107], v[160:163], v[230:233], v[104:107]
	v_mfma_f32_16x16x32_bf16 v[92:95], v[152:155], v[238:241], v[92:95]
	v_mfma_f32_16x16x32_bf16 v[88:91], v[160:163], v[238:241], v[88:91]
	v_mfma_f32_16x16x32_bf16 v[76:79], v[152:155], v[246:249], v[76:79]
	v_mfma_f32_16x16x32_bf16 v[72:75], v[160:163], v[246:249], v[72:75]
	s_setprio 0
	s_setprio 1
	v_mfma_f32_16x16x32_bf16 v[118:121], v[164:167], v[180:183], v[118:121]
	v_mfma_f32_16x16x32_bf16 v[114:117], v[172:175], v[180:183], v[114:117]
	v_mfma_f32_16x16x32_bf16 v[100:103], v[164:167], v[208:211], v[100:103]
	v_mfma_f32_16x16x32_bf16 v[96:99], v[172:175], v[208:211], v[96:99]
	v_mfma_f32_16x16x32_bf16 v[84:87], v[164:167], v[234:237], v[84:87]
	v_mfma_f32_16x16x32_bf16 v[80:83], v[172:175], v[234:237], v[80:83]
	v_mfma_f32_16x16x32_bf16 v[68:71], v[164:167], v[242:245], v[68:71]
	v_mfma_f32_16x16x32_bf16 v[64:67], v[172:175], v[242:245], v[64:67]
	v_mfma_f32_16x16x32_bf16 v[118:121], v[168:171], v[184:187], v[118:121]
	v_mfma_f32_16x16x32_bf16 v[114:117], v[176:179], v[184:187], v[114:117]
	v_mfma_f32_16x16x32_bf16 v[100:103], v[168:171], v[230:233], v[100:103]
	v_mfma_f32_16x16x32_bf16 v[96:99], v[176:179], v[230:233], v[96:99]
	v_mfma_f32_16x16x32_bf16 v[84:87], v[168:171], v[238:241], v[84:87]
	v_mfma_f32_16x16x32_bf16 v[80:83], v[176:179], v[238:241], v[80:83]
	v_mfma_f32_16x16x32_bf16 v[68:71], v[168:171], v[246:249], v[68:71]
	v_mfma_f32_16x16x32_bf16 v[64:67], v[176:179], v[246:249], v[64:67]
	s_setprio 0
	s_barrier
	s_add_i32 s30, s57, s39
	s_mov_b32 m0, s30
	ds_read_b128 v[180:183], v151 offset:49152
	ds_read_b128 v[184:187], v151 offset:50176
	ds_read_b128 v[208:211], v151 offset:51200
	ds_read_b128 v[230:233], v151 offset:52224
	ds_read_b128 v[234:237], v151 offset:53248
	ds_read_b128 v[238:241], v151 offset:54272
	ds_read_b128 v[242:245], v151 offset:55296
	ds_read_b128 v[246:249], v151 offset:56320
	s_add_u32 s98, s28, 0x80
	s_addc_u32 s99, s29, 0
	global_load_lds_dwordx4 v112, s[98:99]
	s_add_i32 m0, s30, 0x2000
	s_add_u32 s28, s28, 0x40080
	v_lshl_add_u64 v[188:189], v[212:213], 0, s[96:97]
	s_addc_u32 s29, s29, 0
	s_add_i32 s30, s58, s39
	global_load_lds_dwordx4 v[188:189], off
	s_mov_b32 m0, s30
	s_nop 0
	global_load_lds_dwordx4 v112, s[28:29]
	s_add_i32 m0, s30, 0x2000
	s_nop 0
	global_load_lds_dwordx4 v134, s[28:29]
	v_lshl_add_u64 v[188:189], v[250:251], 0, s[96:97]
	s_mov_b32 m0, s43
	s_nop 0
	global_load_lds_dwordx4 v[188:189], off
	v_lshl_add_u64 v[188:189], v[252:253], 0, s[96:97]
	s_mov_b32 m0, s44
	s_nop 0
	global_load_lds_dwordx4 v[188:189], off
	s_waitcnt vmcnt(8)
	s_waitcnt lgkmcnt(0)
	s_barrier
	s_setprio 1
	s_waitcnt lgkmcnt(0)
	v_mfma_f32_16x16x32_bf16 v[60:63], v[142:145], v[180:183], v[60:63]
	v_mfma_f32_16x16x32_bf16 v[56:59], v[156:159], v[180:183], v[56:59]
	v_mfma_f32_16x16x32_bf16 v[44:47], v[142:145], v[208:211], v[44:47]
	v_mfma_f32_16x16x32_bf16 v[40:43], v[156:159], v[208:211], v[40:43]
	v_mfma_f32_16x16x32_bf16 v[28:31], v[142:145], v[234:237], v[28:31]
	v_mfma_f32_16x16x32_bf16 v[24:27], v[156:159], v[234:237], v[24:27]
	v_mfma_f32_16x16x32_bf16 v[12:15], v[142:145], v[242:245], v[12:15]
	v_mfma_f32_16x16x32_bf16 v[8:11], v[156:159], v[242:245], v[8:11]
	v_mfma_f32_16x16x32_bf16 v[60:63], v[152:155], v[184:187], v[60:63]
	v_mfma_f32_16x16x32_bf16 v[56:59], v[160:163], v[184:187], v[56:59]
	v_mfma_f32_16x16x32_bf16 v[44:47], v[152:155], v[230:233], v[44:47]
	v_mfma_f32_16x16x32_bf16 v[40:43], v[160:163], v[230:233], v[40:43]
	v_mfma_f32_16x16x32_bf16 v[28:31], v[152:155], v[238:241], v[28:31]
	v_mfma_f32_16x16x32_bf16 v[24:27], v[160:163], v[238:241], v[24:27]
	v_mfma_f32_16x16x32_bf16 v[12:15], v[152:155], v[246:249], v[12:15]
	v_mfma_f32_16x16x32_bf16 v[8:11], v[160:163], v[246:249], v[8:11]
	s_setprio 0
	s_setprio 1
	v_mfma_f32_16x16x32_bf16 v[52:55], v[164:167], v[180:183], v[52:55]
	v_mfma_f32_16x16x32_bf16 v[48:51], v[172:175], v[180:183], v[48:51]
	v_mfma_f32_16x16x32_bf16 v[36:39], v[164:167], v[208:211], v[36:39]
	v_mfma_f32_16x16x32_bf16 v[32:35], v[172:175], v[208:211], v[32:35]
	v_mfma_f32_16x16x32_bf16 v[20:23], v[164:167], v[234:237], v[20:23]
	v_mfma_f32_16x16x32_bf16 v[16:19], v[172:175], v[234:237], v[16:19]
	v_mfma_f32_16x16x32_bf16 v[4:7], v[164:167], v[242:245], v[4:7]
	v_mfma_f32_16x16x32_bf16 v[0:3], v[172:175], v[242:245], v[0:3]
	v_mfma_f32_16x16x32_bf16 v[52:55], v[168:171], v[184:187], v[52:55]
	v_mfma_f32_16x16x32_bf16 v[48:51], v[176:179], v[184:187], v[48:51]
	v_mfma_f32_16x16x32_bf16 v[36:39], v[168:171], v[230:233], v[36:39]
	v_mfma_f32_16x16x32_bf16 v[32:35], v[176:179], v[230:233], v[32:35]
	v_mfma_f32_16x16x32_bf16 v[20:23], v[168:171], v[238:241], v[20:23]
	v_mfma_f32_16x16x32_bf16 v[16:19], v[176:179], v[238:241], v[16:19]
	v_mfma_f32_16x16x32_bf16 v[4:7], v[168:171], v[246:249], v[4:7]
	v_mfma_f32_16x16x32_bf16 v[0:3], v[176:179], v[246:249], v[0:3]
	s_setprio 0
	s_barrier
	s_add_i32 s56, s56, 2
	s_add_u32 s54, s54, 0x100
	s_addc_u32 s55, s55, 0
	s_add_u32 s6, s6, 0x100
	s_addc_u32 s7, s7, 0
	s_cmp_gt_u32 s56, 13
	s_cbranch_scc0 .LBB0_2369
	s_branch .Lpeel_exit_2369
	.p2align 6
